# v41 plus: s_setprio 1 moved before the pre-MMA barrier and the already-satisfied s_waitcnt lgkmcnt(0) after it dropped, so the first MFMA follows the barrier directly
# speedup vs baseline: 1.0043x; 1.0006x over previous
.LBB0_307:
	s_add_u32 vcc_lo, s82, 0x80
	s_addc_u32 vcc_hi, s83, 0
	s_add_u32 s82, s42, 0x100
	s_addc_u32 s83, s43, 0
	s_mov_b32 s42, 0
	s_add_i32 s72, s42, 2
	s_add_u32 s73, vcc_lo, 0x80
	s_addc_u32 s43, vcc_hi, 0
	s_add_i32 s45, 0, 0x10000
	s_cmp_eq_u32 s63, s42
	s_cselect_b32 s43, s9, s43
	s_cselect_b32 s42, s8, s73
	v_add_u32_e32 v140, s45, v143
	s_cselect_b32 s75, s91, s83
	s_cselect_b32 s74, s90, s82
	s_add_i32 s73, 0, 0x14000
	ds_read_b128 v[146:149], v140
	ds_read_b128 v[150:153], v140 offset:1024
	ds_read_b128 v[154:157], v140 offset:2048
	ds_read_b128 v[158:161], v140 offset:3072
	v_add_u32_e32 v140, s73, v143
	ds_read_b128 v[162:165], v140
	ds_read_b128 v[166:169], v140 offset:1024
	ds_read_b128 v[170:173], v140 offset:2048
	ds_read_b128 v[174:177], v140 offset:3072
	v_lshl_add_u64 v[140:141], vcc, 0, v[136:137]
	s_add_i32 m0, s59, 0xc000
	ds_read_b128 v[178:181], v145
	ds_read_b128 v[182:185], v145 offset:1024
	ds_read_b128 v[186:189], v145 offset:2048
	ds_read_b128 v[190:193], v145 offset:3072
	ds_read_b128 v[202:205], v145 offset:4096
	ds_read_b128 v[206:209], v145 offset:5120
	ds_read_b128 v[220:223], v145 offset:6144
	ds_read_b128 v[224:227], v145 offset:7168
	global_load_lds_dwordx4 v[140:141], off
	v_lshl_add_u64 v[140:141], vcc, 0, v[138:139]
	s_add_i32 m0, s59, 0xe000
	s_nop 0
	global_load_lds_dwordx4 v[140:141], off
	s_waitcnt vmcnt(8)
	s_waitcnt lgkmcnt(0)
	s_setprio 1
	s_barrier
	v_mfma_f32_16x16x32_bf16 v[126:129], v[146:149], v[178:181], 0
	v_mfma_f32_16x16x32_bf16 v[122:125], v[154:157], v[178:181], 0
	v_mfma_f32_16x16x32_bf16 v[118:121], v[146:149], v[186:189], 0
	v_mfma_f32_16x16x32_bf16 v[110:113], v[154:157], v[186:189], 0
	v_mfma_f32_16x16x32_bf16 v[102:105], v[146:149], v[202:205], 0
	v_mfma_f32_16x16x32_bf16 v[94:97], v[154:157], v[202:205], 0
	v_mfma_f32_16x16x32_bf16 v[86:89], v[146:149], v[220:223], 0
	v_mfma_f32_16x16x32_bf16 v[78:81], v[154:157], v[220:223], 0
	v_mfma_f32_16x16x32_bf16 v[126:129], v[150:153], v[182:185], v[126:129]
	v_mfma_f32_16x16x32_bf16 v[122:125], v[158:161], v[182:185], v[122:125]
	v_mfma_f32_16x16x32_bf16 v[118:121], v[150:153], v[190:193], v[118:121]
	v_mfma_f32_16x16x32_bf16 v[110:113], v[158:161], v[190:193], v[110:113]
	v_mfma_f32_16x16x32_bf16 v[102:105], v[150:153], v[206:209], v[102:105]
	v_mfma_f32_16x16x32_bf16 v[94:97], v[158:161], v[206:209], v[94:97]
	v_mfma_f32_16x16x32_bf16 v[86:89], v[150:153], v[224:227], v[86:89]
	v_mfma_f32_16x16x32_bf16 v[78:81], v[158:161], v[224:227], v[78:81]
	v_mfma_f32_16x16x32_bf16 v[114:117], v[162:165], v[178:181], 0
	v_mfma_f32_16x16x32_bf16 v[106:109], v[170:173], v[178:181], 0
	v_mfma_f32_16x16x32_bf16 v[98:101], v[162:165], v[186:189], 0
	v_mfma_f32_16x16x32_bf16 v[90:93], v[170:173], v[186:189], 0
	v_mfma_f32_16x16x32_bf16 v[82:85], v[162:165], v[202:205], 0
	v_mfma_f32_16x16x32_bf16 v[74:77], v[170:173], v[202:205], 0
	v_mfma_f32_16x16x32_bf16 v[70:73], v[162:165], v[220:223], 0
	v_mfma_f32_16x16x32_bf16 v[66:69], v[170:173], v[220:223], 0
	v_mfma_f32_16x16x32_bf16 v[114:117], v[166:169], v[182:185], v[114:117]
	v_mfma_f32_16x16x32_bf16 v[106:109], v[174:177], v[182:185], v[106:109]
	v_mfma_f32_16x16x32_bf16 v[98:101], v[166:169], v[190:193], v[98:101]
	v_mfma_f32_16x16x32_bf16 v[90:93], v[174:177], v[190:193], v[90:93]
	v_mfma_f32_16x16x32_bf16 v[82:85], v[166:169], v[206:209], v[82:85]
	v_mfma_f32_16x16x32_bf16 v[74:77], v[174:177], v[206:209], v[74:77]
	v_mfma_f32_16x16x32_bf16 v[70:73], v[166:169], v[224:227], v[70:73]
	v_mfma_f32_16x16x32_bf16 v[66:69], v[174:177], v[224:227], v[66:69]
	s_setprio 0
	s_barrier
	s_add_i32 s45, s45, s54
	v_lshl_add_u64 v[140:141], s[74:75], 0, v[0:1]
	s_mov_b32 m0, s45
	ds_read_b128 v[178:181], v145 offset:16384
	ds_read_b128 v[182:185], v145 offset:17408
	ds_read_b128 v[186:189], v145 offset:18432
	ds_read_b128 v[190:193], v145 offset:19456
	ds_read_b128 v[202:205], v145 offset:20480
	ds_read_b128 v[206:209], v145 offset:21504
	ds_read_b128 v[220:223], v145 offset:22528
	ds_read_b128 v[224:227], v145 offset:23552
	global_load_lds_dwordx4 v[140:141], off
	s_add_i32 m0, s45, 0x2000
	v_lshl_add_u64 v[194:195], s[74:75], 0, v[134:135]
	s_add_u32 s74, s74, s80
	s_addc_u32 s75, s75, 0
	s_add_i32 s45, s73, s54
	global_load_lds_dwordx4 v[194:195], off
	v_lshl_add_u64 v[198:199], s[74:75], 0, v[0:1]
	s_mov_b32 m0, s45
	v_lshl_add_u64 v[200:201], s[74:75], 0, v[134:135]
	global_load_lds_dwordx4 v[198:199], off
	s_add_i32 m0, s45, 0x2000
	v_lshl_add_u64 v[210:211], s[42:43], 0, v[130:131]
	global_load_lds_dwordx4 v[200:201], off
	s_mov_b32 m0, s59
	v_lshl_add_u64 v[212:213], s[42:43], 0, v[132:133]
	global_load_lds_dwordx4 v[210:211], off
	s_mov_b32 m0, s60
	s_nop 0
	global_load_lds_dwordx4 v[212:213], off
	s_waitcnt vmcnt(8)
	s_waitcnt lgkmcnt(0)
	s_setprio 1
	s_barrier
	v_mfma_f32_16x16x32_bf16 v[62:65], v[146:149], v[178:181], 0
	v_mfma_f32_16x16x32_bf16 v[58:61], v[154:157], v[178:181], 0
	v_mfma_f32_16x16x32_bf16 v[54:57], v[146:149], v[186:189], 0
	v_mfma_f32_16x16x32_bf16 v[46:49], v[154:157], v[186:189], 0
	v_mfma_f32_16x16x32_bf16 v[38:41], v[146:149], v[202:205], 0
	v_mfma_f32_16x16x32_bf16 v[30:33], v[154:157], v[202:205], 0
	v_mfma_f32_16x16x32_bf16 v[22:25], v[146:149], v[220:223], 0
	v_mfma_f32_16x16x32_bf16 v[14:17], v[154:157], v[220:223], 0
	v_mfma_f32_16x16x32_bf16 v[62:65], v[150:153], v[182:185], v[62:65]
	v_mfma_f32_16x16x32_bf16 v[58:61], v[158:161], v[182:185], v[58:61]
	v_mfma_f32_16x16x32_bf16 v[54:57], v[150:153], v[190:193], v[54:57]
	v_mfma_f32_16x16x32_bf16 v[46:49], v[158:161], v[190:193], v[46:49]
	v_mfma_f32_16x16x32_bf16 v[38:41], v[150:153], v[206:209], v[38:41]
	v_mfma_f32_16x16x32_bf16 v[30:33], v[158:161], v[206:209], v[30:33]
	v_mfma_f32_16x16x32_bf16 v[22:25], v[150:153], v[224:227], v[22:25]
	v_mfma_f32_16x16x32_bf16 v[14:17], v[158:161], v[224:227], v[14:17]
	v_mfma_f32_16x16x32_bf16 v[50:53], v[162:165], v[178:181], 0
	v_mfma_f32_16x16x32_bf16 v[42:45], v[170:173], v[178:181], 0
	v_mfma_f32_16x16x32_bf16 v[34:37], v[162:165], v[186:189], 0
	v_mfma_f32_16x16x32_bf16 v[26:29], v[170:173], v[186:189], 0
	v_mfma_f32_16x16x32_bf16 v[18:21], v[162:165], v[202:205], 0
	v_mfma_f32_16x16x32_bf16 v[10:13], v[170:173], v[202:205], 0
	v_mfma_f32_16x16x32_bf16 v[6:9], v[162:165], v[220:223], 0
	v_mfma_f32_16x16x32_bf16 v[2:5], v[170:173], v[220:223], 0
	v_mfma_f32_16x16x32_bf16 v[50:53], v[166:169], v[182:185], v[50:53]
	v_mfma_f32_16x16x32_bf16 v[42:45], v[174:177], v[182:185], v[42:45]
	v_mfma_f32_16x16x32_bf16 v[34:37], v[166:169], v[190:193], v[34:37]
	v_mfma_f32_16x16x32_bf16 v[26:29], v[174:177], v[190:193], v[26:29]
	v_mfma_f32_16x16x32_bf16 v[18:21], v[166:169], v[206:209], v[18:21]
	v_mfma_f32_16x16x32_bf16 v[10:13], v[174:177], v[206:209], v[10:13]
	v_mfma_f32_16x16x32_bf16 v[6:9], v[166:169], v[224:227], v[6:9]
	v_mfma_f32_16x16x32_bf16 v[2:5], v[174:177], v[224:227], v[2:5]
	s_setprio 0
	s_barrier
	s_add_i32 s45, 0, 0x18000
	s_add_i32 s73, 0, 0x1c000
	v_add_u32_e32 v158, s45, v143
	v_add_u32_e32 v174, s73, v143
	ds_read_b128 v[146:149], v158
	ds_read_b128 v[150:153], v158 offset:1024
	ds_read_b128 v[154:157], v158 offset:2048
	ds_read_b128 v[158:161], v158 offset:3072
	ds_read_b128 v[162:165], v174
	ds_read_b128 v[166:169], v174 offset:1024
	ds_read_b128 v[170:173], v174 offset:2048
	ds_read_b128 v[174:177], v174 offset:3072
	s_add_u32 s42, s42, s80
	s_addc_u32 s43, s43, 0
	s_mov_b32 m0, s61
	v_lshl_add_u64 v[214:215], s[42:43], 0, v[130:131]
	ds_read_b128 v[178:181], v145 offset:32768
	ds_read_b128 v[182:185], v145 offset:33792
	ds_read_b128 v[186:189], v145 offset:34816
	ds_read_b128 v[190:193], v145 offset:35840
	ds_read_b128 v[202:205], v145 offset:36864
	ds_read_b128 v[206:209], v145 offset:37888
	ds_read_b128 v[220:223], v145 offset:38912
	ds_read_b128 v[224:227], v145 offset:39936
	global_load_lds_dwordx4 v[214:215], off
	v_lshl_add_u64 v[214:215], s[42:43], 0, v[132:133]
	s_mov_b32 m0, s62
	s_nop 0
	global_load_lds_dwordx4 v[214:215], off
	s_waitcnt vmcnt(8)
	s_waitcnt lgkmcnt(0)
	s_setprio 1
	s_barrier
	v_mfma_f32_16x16x32_bf16 v[126:129], v[146:149], v[178:181], v[126:129]
	v_mfma_f32_16x16x32_bf16 v[122:125], v[154:157], v[178:181], v[122:125]
	v_mfma_f32_16x16x32_bf16 v[118:121], v[146:149], v[186:189], v[118:121]
	v_mfma_f32_16x16x32_bf16 v[110:113], v[154:157], v[186:189], v[110:113]
	v_mfma_f32_16x16x32_bf16 v[102:105], v[146:149], v[202:205], v[102:105]
	v_mfma_f32_16x16x32_bf16 v[94:97], v[154:157], v[202:205], v[94:97]
	v_mfma_f32_16x16x32_bf16 v[86:89], v[146:149], v[220:223], v[86:89]
	v_mfma_f32_16x16x32_bf16 v[78:81], v[154:157], v[220:223], v[78:81]
	v_mfma_f32_16x16x32_bf16 v[126:129], v[150:153], v[182:185], v[126:129]
	v_mfma_f32_16x16x32_bf16 v[122:125], v[158:161], v[182:185], v[122:125]
	v_mfma_f32_16x16x32_bf16 v[118:121], v[150:153], v[190:193], v[118:121]
	v_mfma_f32_16x16x32_bf16 v[110:113], v[158:161], v[190:193], v[110:113]
	v_mfma_f32_16x16x32_bf16 v[102:105], v[150:153], v[206:209], v[102:105]
	v_mfma_f32_16x16x32_bf16 v[94:97], v[158:161], v[206:209], v[94:97]
	v_mfma_f32_16x16x32_bf16 v[86:89], v[150:153], v[224:227], v[86:89]
	v_mfma_f32_16x16x32_bf16 v[78:81], v[158:161], v[224:227], v[78:81]
	v_mfma_f32_16x16x32_bf16 v[114:117], v[162:165], v[178:181], v[114:117]
	v_mfma_f32_16x16x32_bf16 v[106:109], v[170:173], v[178:181], v[106:109]
	v_mfma_f32_16x16x32_bf16 v[98:101], v[162:165], v[186:189], v[98:101]
	v_mfma_f32_16x16x32_bf16 v[90:93], v[170:173], v[186:189], v[90:93]
	v_mfma_f32_16x16x32_bf16 v[82:85], v[162:165], v[202:205], v[82:85]
	v_mfma_f32_16x16x32_bf16 v[74:77], v[170:173], v[202:205], v[74:77]
	v_mfma_f32_16x16x32_bf16 v[70:73], v[162:165], v[220:223], v[70:73]
	v_mfma_f32_16x16x32_bf16 v[66:69], v[170:173], v[220:223], v[66:69]
	v_mfma_f32_16x16x32_bf16 v[114:117], v[166:169], v[182:185], v[114:117]
	v_mfma_f32_16x16x32_bf16 v[106:109], v[174:177], v[182:185], v[106:109]
	v_mfma_f32_16x16x32_bf16 v[98:101], v[166:169], v[190:193], v[98:101]
	v_mfma_f32_16x16x32_bf16 v[90:93], v[174:177], v[190:193], v[90:93]
	v_mfma_f32_16x16x32_bf16 v[82:85], v[166:169], v[206:209], v[82:85]
	v_mfma_f32_16x16x32_bf16 v[74:77], v[174:177], v[206:209], v[74:77]
	v_mfma_f32_16x16x32_bf16 v[70:73], v[166:169], v[224:227], v[70:73]
	v_mfma_f32_16x16x32_bf16 v[66:69], v[174:177], v[224:227], v[66:69]
	s_setprio 0
	s_barrier
	s_add_i32 s42, s45, s54
	v_lshl_add_u64 v[140:141], v[140:141], 0, s[84:85]
	s_mov_b32 m0, s42
	ds_read_b128 v[178:181], v145 offset:49152
	ds_read_b128 v[182:185], v145 offset:50176
	ds_read_b128 v[186:189], v145 offset:51200
	ds_read_b128 v[190:193], v145 offset:52224
	ds_read_b128 v[202:205], v145 offset:53248
	ds_read_b128 v[206:209], v145 offset:54272
	ds_read_b128 v[220:223], v145 offset:55296
	ds_read_b128 v[224:227], v145 offset:56320
	global_load_lds_dwordx4 v[140:141], off
	v_lshl_add_u64 v[140:141], v[194:195], 0, s[84:85]
	s_add_i32 m0, s42, 0x2000
	s_add_i32 s42, s73, s54
	global_load_lds_dwordx4 v[140:141], off
	v_lshl_add_u64 v[140:141], v[198:199], 0, s[84:85]
	s_mov_b32 m0, s42
	s_nop 0
	global_load_lds_dwordx4 v[140:141], off
	v_lshl_add_u64 v[140:141], v[200:201], 0, s[84:85]
	s_add_i32 m0, s42, 0x2000
	s_nop 0
	global_load_lds_dwordx4 v[140:141], off
	v_lshl_add_u64 v[140:141], v[210:211], 0, s[84:85]
	s_mov_b32 m0, s64
	s_nop 0
	global_load_lds_dwordx4 v[140:141], off
	v_lshl_add_u64 v[140:141], v[212:213], 0, s[84:85]
	s_mov_b32 m0, s65
	s_nop 0
	global_load_lds_dwordx4 v[140:141], off
	s_waitcnt vmcnt(8)
	s_waitcnt lgkmcnt(0)
	s_setprio 1
	s_barrier
	v_mfma_f32_16x16x32_bf16 v[62:65], v[146:149], v[178:181], v[62:65]
	v_mfma_f32_16x16x32_bf16 v[58:61], v[154:157], v[178:181], v[58:61]
	v_mfma_f32_16x16x32_bf16 v[54:57], v[146:149], v[186:189], v[54:57]
	v_mfma_f32_16x16x32_bf16 v[46:49], v[154:157], v[186:189], v[46:49]
	v_mfma_f32_16x16x32_bf16 v[38:41], v[146:149], v[202:205], v[38:41]
	v_mfma_f32_16x16x32_bf16 v[30:33], v[154:157], v[202:205], v[30:33]
	v_mfma_f32_16x16x32_bf16 v[22:25], v[146:149], v[220:223], v[22:25]
	v_mfma_f32_16x16x32_bf16 v[14:17], v[154:157], v[220:223], v[14:17]
	v_mfma_f32_16x16x32_bf16 v[62:65], v[150:153], v[182:185], v[62:65]
	v_mfma_f32_16x16x32_bf16 v[58:61], v[158:161], v[182:185], v[58:61]
	v_mfma_f32_16x16x32_bf16 v[54:57], v[150:153], v[190:193], v[54:57]
	v_mfma_f32_16x16x32_bf16 v[46:49], v[158:161], v[190:193], v[46:49]
	v_mfma_f32_16x16x32_bf16 v[38:41], v[150:153], v[206:209], v[38:41]
	v_mfma_f32_16x16x32_bf16 v[30:33], v[158:161], v[206:209], v[30:33]
	v_mfma_f32_16x16x32_bf16 v[22:25], v[150:153], v[224:227], v[22:25]
	v_mfma_f32_16x16x32_bf16 v[14:17], v[158:161], v[224:227], v[14:17]
	v_mfma_f32_16x16x32_bf16 v[50:53], v[162:165], v[178:181], v[50:53]
	v_mfma_f32_16x16x32_bf16 v[42:45], v[170:173], v[178:181], v[42:45]
	v_mfma_f32_16x16x32_bf16 v[34:37], v[162:165], v[186:189], v[34:37]
	v_mfma_f32_16x16x32_bf16 v[26:29], v[170:173], v[186:189], v[26:29]
	v_mfma_f32_16x16x32_bf16 v[18:21], v[162:165], v[202:205], v[18:21]
	v_mfma_f32_16x16x32_bf16 v[10:13], v[170:173], v[202:205], v[10:13]
	v_mfma_f32_16x16x32_bf16 v[6:9], v[162:165], v[220:223], v[6:9]
	v_mfma_f32_16x16x32_bf16 v[2:5], v[170:173], v[220:223], v[2:5]
	v_mfma_f32_16x16x32_bf16 v[50:53], v[166:169], v[182:185], v[50:53]
	v_mfma_f32_16x16x32_bf16 v[42:45], v[174:177], v[182:185], v[42:45]
	v_mfma_f32_16x16x32_bf16 v[34:37], v[166:169], v[190:193], v[34:37]
	v_mfma_f32_16x16x32_bf16 v[26:29], v[174:177], v[190:193], v[26:29]
	v_mfma_f32_16x16x32_bf16 v[18:21], v[166:169], v[206:209], v[18:21]
	v_mfma_f32_16x16x32_bf16 v[10:13], v[174:177], v[206:209], v[10:13]
	v_mfma_f32_16x16x32_bf16 v[6:9], v[166:169], v[224:227], v[6:9]
	v_mfma_f32_16x16x32_bf16 v[2:5], v[174:177], v[224:227], v[2:5]
	s_setprio 0
	s_barrier
	s_add_u32 vcc_lo, vcc_lo, 0x100
	s_addc_u32 vcc_hi, vcc_hi, 0
	s_add_u32 s82, s82, 0x100
	s_addc_u32 s83, s83, 0
	s_cmp_ge_u32 s72, s66
	s_mov_b32 s42, s72
	s_cbranch_scc1 .Lpeel_exit_bf
.LBB0_308:
	s_add_i32 s72, s42, 2
	s_add_u32 s73, vcc_lo, 0x80
	s_addc_u32 s43, vcc_hi, 0
	s_add_i32 s45, 0, 0x10000
	s_cmp_eq_u32 s63, s42
	s_cselect_b32 s43, s9, s43
	s_cselect_b32 s42, s8, s73
	v_add_u32_e32 v140, s45, v143
	s_cselect_b32 s75, s91, s83
	s_cselect_b32 s74, s90, s82
	s_add_i32 s73, 0, 0x14000
	ds_read_b128 v[146:149], v140
	ds_read_b128 v[150:153], v140 offset:1024
	ds_read_b128 v[154:157], v140 offset:2048
	ds_read_b128 v[158:161], v140 offset:3072
	v_add_u32_e32 v140, s73, v143
	ds_read_b128 v[162:165], v140
	ds_read_b128 v[166:169], v140 offset:1024
	ds_read_b128 v[170:173], v140 offset:2048
	ds_read_b128 v[174:177], v140 offset:3072
	v_lshl_add_u64 v[140:141], vcc, 0, v[136:137]
	s_add_i32 m0, s59, 0xc000
	ds_read_b128 v[178:181], v145
	ds_read_b128 v[182:185], v145 offset:1024
	ds_read_b128 v[186:189], v145 offset:2048
	ds_read_b128 v[190:193], v145 offset:3072
	ds_read_b128 v[202:205], v145 offset:4096
	ds_read_b128 v[206:209], v145 offset:5120
	ds_read_b128 v[220:223], v145 offset:6144
	ds_read_b128 v[224:227], v145 offset:7168
	global_load_lds_dwordx4 v[140:141], off
	v_lshl_add_u64 v[140:141], vcc, 0, v[138:139]
	s_add_i32 m0, s59, 0xe000
	s_nop 0
	global_load_lds_dwordx4 v[140:141], off
	s_waitcnt vmcnt(8)
	s_waitcnt lgkmcnt(0)
	s_setprio 1
	s_barrier
	v_mfma_f32_16x16x32_bf16 v[126:129], v[146:149], v[178:181], v[126:129]
	v_mfma_f32_16x16x32_bf16 v[122:125], v[154:157], v[178:181], v[122:125]
	v_mfma_f32_16x16x32_bf16 v[118:121], v[146:149], v[186:189], v[118:121]
	v_mfma_f32_16x16x32_bf16 v[110:113], v[154:157], v[186:189], v[110:113]
	v_mfma_f32_16x16x32_bf16 v[102:105], v[146:149], v[202:205], v[102:105]
	v_mfma_f32_16x16x32_bf16 v[94:97], v[154:157], v[202:205], v[94:97]
	v_mfma_f32_16x16x32_bf16 v[86:89], v[146:149], v[220:223], v[86:89]
	v_mfma_f32_16x16x32_bf16 v[78:81], v[154:157], v[220:223], v[78:81]
	v_mfma_f32_16x16x32_bf16 v[126:129], v[150:153], v[182:185], v[126:129]
	v_mfma_f32_16x16x32_bf16 v[122:125], v[158:161], v[182:185], v[122:125]
	v_mfma_f32_16x16x32_bf16 v[118:121], v[150:153], v[190:193], v[118:121]
	v_mfma_f32_16x16x32_bf16 v[110:113], v[158:161], v[190:193], v[110:113]
	v_mfma_f32_16x16x32_bf16 v[102:105], v[150:153], v[206:209], v[102:105]
	v_mfma_f32_16x16x32_bf16 v[94:97], v[158:161], v[206:209], v[94:97]
	v_mfma_f32_16x16x32_bf16 v[86:89], v[150:153], v[224:227], v[86:89]
	v_mfma_f32_16x16x32_bf16 v[78:81], v[158:161], v[224:227], v[78:81]
	v_mfma_f32_16x16x32_bf16 v[114:117], v[162:165], v[178:181], v[114:117]
	v_mfma_f32_16x16x32_bf16 v[106:109], v[170:173], v[178:181], v[106:109]
	v_mfma_f32_16x16x32_bf16 v[98:101], v[162:165], v[186:189], v[98:101]
	v_mfma_f32_16x16x32_bf16 v[90:93], v[170:173], v[186:189], v[90:93]
	v_mfma_f32_16x16x32_bf16 v[82:85], v[162:165], v[202:205], v[82:85]
	v_mfma_f32_16x16x32_bf16 v[74:77], v[170:173], v[202:205], v[74:77]
	v_mfma_f32_16x16x32_bf16 v[70:73], v[162:165], v[220:223], v[70:73]
	v_mfma_f32_16x16x32_bf16 v[66:69], v[170:173], v[220:223], v[66:69]
	v_mfma_f32_16x16x32_bf16 v[114:117], v[166:169], v[182:185], v[114:117]
	v_mfma_f32_16x16x32_bf16 v[106:109], v[174:177], v[182:185], v[106:109]
	v_mfma_f32_16x16x32_bf16 v[98:101], v[166:169], v[190:193], v[98:101]
	v_mfma_f32_16x16x32_bf16 v[90:93], v[174:177], v[190:193], v[90:93]
	v_mfma_f32_16x16x32_bf16 v[82:85], v[166:169], v[206:209], v[82:85]
	v_mfma_f32_16x16x32_bf16 v[74:77], v[174:177], v[206:209], v[74:77]
	v_mfma_f32_16x16x32_bf16 v[70:73], v[166:169], v[224:227], v[70:73]
	v_mfma_f32_16x16x32_bf16 v[66:69], v[174:177], v[224:227], v[66:69]
	s_setprio 0
	s_barrier
	s_add_i32 s45, s45, s54
	v_lshl_add_u64 v[140:141], s[74:75], 0, v[0:1]
	s_mov_b32 m0, s45
	ds_read_b128 v[178:181], v145 offset:16384
	ds_read_b128 v[182:185], v145 offset:17408
	ds_read_b128 v[186:189], v145 offset:18432
	ds_read_b128 v[190:193], v145 offset:19456
	ds_read_b128 v[202:205], v145 offset:20480
	ds_read_b128 v[206:209], v145 offset:21504
	ds_read_b128 v[220:223], v145 offset:22528
	ds_read_b128 v[224:227], v145 offset:23552
	global_load_lds_dwordx4 v[140:141], off
	s_add_i32 m0, s45, 0x2000
	v_lshl_add_u64 v[194:195], s[74:75], 0, v[134:135]
	s_add_u32 s74, s74, s80
	s_addc_u32 s75, s75, 0
	s_add_i32 s45, s73, s54
	global_load_lds_dwordx4 v[194:195], off
	v_lshl_add_u64 v[198:199], s[74:75], 0, v[0:1]
	s_mov_b32 m0, s45
	v_lshl_add_u64 v[200:201], s[74:75], 0, v[134:135]
	global_load_lds_dwordx4 v[198:199], off
	s_add_i32 m0, s45, 0x2000
	v_lshl_add_u64 v[210:211], s[42:43], 0, v[130:131]
	global_load_lds_dwordx4 v[200:201], off
	s_mov_b32 m0, s59
	v_lshl_add_u64 v[212:213], s[42:43], 0, v[132:133]
	global_load_lds_dwordx4 v[210:211], off
	s_mov_b32 m0, s60
	s_nop 0
	global_load_lds_dwordx4 v[212:213], off
	s_waitcnt vmcnt(8)
	s_waitcnt lgkmcnt(0)
	s_setprio 1
	s_barrier
	v_mfma_f32_16x16x32_bf16 v[62:65], v[146:149], v[178:181], v[62:65]
	v_mfma_f32_16x16x32_bf16 v[58:61], v[154:157], v[178:181], v[58:61]
	v_mfma_f32_16x16x32_bf16 v[54:57], v[146:149], v[186:189], v[54:57]
	v_mfma_f32_16x16x32_bf16 v[46:49], v[154:157], v[186:189], v[46:49]
	v_mfma_f32_16x16x32_bf16 v[38:41], v[146:149], v[202:205], v[38:41]
	v_mfma_f32_16x16x32_bf16 v[30:33], v[154:157], v[202:205], v[30:33]
	v_mfma_f32_16x16x32_bf16 v[22:25], v[146:149], v[220:223], v[22:25]
	v_mfma_f32_16x16x32_bf16 v[14:17], v[154:157], v[220:223], v[14:17]
	v_mfma_f32_16x16x32_bf16 v[62:65], v[150:153], v[182:185], v[62:65]
	v_mfma_f32_16x16x32_bf16 v[58:61], v[158:161], v[182:185], v[58:61]
	v_mfma_f32_16x16x32_bf16 v[54:57], v[150:153], v[190:193], v[54:57]
	v_mfma_f32_16x16x32_bf16 v[46:49], v[158:161], v[190:193], v[46:49]
	v_mfma_f32_16x16x32_bf16 v[38:41], v[150:153], v[206:209], v[38:41]
	v_mfma_f32_16x16x32_bf16 v[30:33], v[158:161], v[206:209], v[30:33]
	v_mfma_f32_16x16x32_bf16 v[22:25], v[150:153], v[224:227], v[22:25]
	v_mfma_f32_16x16x32_bf16 v[14:17], v[158:161], v[224:227], v[14:17]
	v_mfma_f32_16x16x32_bf16 v[50:53], v[162:165], v[178:181], v[50:53]
	v_mfma_f32_16x16x32_bf16 v[42:45], v[170:173], v[178:181], v[42:45]
	v_mfma_f32_16x16x32_bf16 v[34:37], v[162:165], v[186:189], v[34:37]
	v_mfma_f32_16x16x32_bf16 v[26:29], v[170:173], v[186:189], v[26:29]
	v_mfma_f32_16x16x32_bf16 v[18:21], v[162:165], v[202:205], v[18:21]
	v_mfma_f32_16x16x32_bf16 v[10:13], v[170:173], v[202:205], v[10:13]
	v_mfma_f32_16x16x32_bf16 v[6:9], v[162:165], v[220:223], v[6:9]
	v_mfma_f32_16x16x32_bf16 v[2:5], v[170:173], v[220:223], v[2:5]
	v_mfma_f32_16x16x32_bf16 v[50:53], v[166:169], v[182:185], v[50:53]
	v_mfma_f32_16x16x32_bf16 v[42:45], v[174:177], v[182:185], v[42:45]
	v_mfma_f32_16x16x32_bf16 v[34:37], v[166:169], v[190:193], v[34:37]
	v_mfma_f32_16x16x32_bf16 v[26:29], v[174:177], v[190:193], v[26:29]
	v_mfma_f32_16x16x32_bf16 v[18:21], v[166:169], v[206:209], v[18:21]
	v_mfma_f32_16x16x32_bf16 v[10:13], v[174:177], v[206:209], v[10:13]
	v_mfma_f32_16x16x32_bf16 v[6:9], v[166:169], v[224:227], v[6:9]
	v_mfma_f32_16x16x32_bf16 v[2:5], v[174:177], v[224:227], v[2:5]
	s_setprio 0
	s_barrier
	s_add_i32 s45, 0, 0x18000
	s_add_i32 s73, 0, 0x1c000
	v_add_u32_e32 v158, s45, v143
	v_add_u32_e32 v174, s73, v143
	ds_read_b128 v[146:149], v158
	ds_read_b128 v[150:153], v158 offset:1024
	ds_read_b128 v[154:157], v158 offset:2048
	ds_read_b128 v[158:161], v158 offset:3072
	ds_read_b128 v[162:165], v174
	ds_read_b128 v[166:169], v174 offset:1024
	ds_read_b128 v[170:173], v174 offset:2048
	ds_read_b128 v[174:177], v174 offset:3072
	s_add_u32 s42, s42, s80
	s_addc_u32 s43, s43, 0
	s_mov_b32 m0, s61
	v_lshl_add_u64 v[214:215], s[42:43], 0, v[130:131]
	ds_read_b128 v[178:181], v145 offset:32768
	ds_read_b128 v[182:185], v145 offset:33792
	ds_read_b128 v[186:189], v145 offset:34816
	ds_read_b128 v[190:193], v145 offset:35840
	ds_read_b128 v[202:205], v145 offset:36864
	ds_read_b128 v[206:209], v145 offset:37888
	ds_read_b128 v[220:223], v145 offset:38912
	ds_read_b128 v[224:227], v145 offset:39936
	global_load_lds_dwordx4 v[214:215], off
	v_lshl_add_u64 v[214:215], s[42:43], 0, v[132:133]
	s_mov_b32 m0, s62
	s_nop 0
	global_load_lds_dwordx4 v[214:215], off
	s_waitcnt vmcnt(8)
	s_waitcnt lgkmcnt(0)
	s_setprio 1
	s_barrier
	v_mfma_f32_16x16x32_bf16 v[126:129], v[146:149], v[178:181], v[126:129]
	v_mfma_f32_16x16x32_bf16 v[122:125], v[154:157], v[178:181], v[122:125]
	v_mfma_f32_16x16x32_bf16 v[118:121], v[146:149], v[186:189], v[118:121]
	v_mfma_f32_16x16x32_bf16 v[110:113], v[154:157], v[186:189], v[110:113]
	v_mfma_f32_16x16x32_bf16 v[102:105], v[146:149], v[202:205], v[102:105]
	v_mfma_f32_16x16x32_bf16 v[94:97], v[154:157], v[202:205], v[94:97]
	v_mfma_f32_16x16x32_bf16 v[86:89], v[146:149], v[220:223], v[86:89]
	v_mfma_f32_16x16x32_bf16 v[78:81], v[154:157], v[220:223], v[78:81]
	v_mfma_f32_16x16x32_bf16 v[126:129], v[150:153], v[182:185], v[126:129]
	v_mfma_f32_16x16x32_bf16 v[122:125], v[158:161], v[182:185], v[122:125]
	v_mfma_f32_16x16x32_bf16 v[118:121], v[150:153], v[190:193], v[118:121]
	v_mfma_f32_16x16x32_bf16 v[110:113], v[158:161], v[190:193], v[110:113]
	v_mfma_f32_16x16x32_bf16 v[102:105], v[150:153], v[206:209], v[102:105]
	v_mfma_f32_16x16x32_bf16 v[94:97], v[158:161], v[206:209], v[94:97]
	v_mfma_f32_16x16x32_bf16 v[86:89], v[150:153], v[224:227], v[86:89]
	v_mfma_f32_16x16x32_bf16 v[78:81], v[158:161], v[224:227], v[78:81]
	v_mfma_f32_16x16x32_bf16 v[114:117], v[162:165], v[178:181], v[114:117]
	v_mfma_f32_16x16x32_bf16 v[106:109], v[170:173], v[178:181], v[106:109]
	v_mfma_f32_16x16x32_bf16 v[98:101], v[162:165], v[186:189], v[98:101]
	v_mfma_f32_16x16x32_bf16 v[90:93], v[170:173], v[186:189], v[90:93]
	v_mfma_f32_16x16x32_bf16 v[82:85], v[162:165], v[202:205], v[82:85]
	v_mfma_f32_16x16x32_bf16 v[74:77], v[170:173], v[202:205], v[74:77]
	v_mfma_f32_16x16x32_bf16 v[70:73], v[162:165], v[220:223], v[70:73]
	v_mfma_f32_16x16x32_bf16 v[66:69], v[170:173], v[220:223], v[66:69]
	v_mfma_f32_16x16x32_bf16 v[114:117], v[166:169], v[182:185], v[114:117]
	v_mfma_f32_16x16x32_bf16 v[106:109], v[174:177], v[182:185], v[106:109]
	v_mfma_f32_16x16x32_bf16 v[98:101], v[166:169], v[190:193], v[98:101]
	v_mfma_f32_16x16x32_bf16 v[90:93], v[174:177], v[190:193], v[90:93]
	v_mfma_f32_16x16x32_bf16 v[82:85], v[166:169], v[206:209], v[82:85]
	v_mfma_f32_16x16x32_bf16 v[74:77], v[174:177], v[206:209], v[74:77]
	v_mfma_f32_16x16x32_bf16 v[70:73], v[166:169], v[224:227], v[70:73]
	v_mfma_f32_16x16x32_bf16 v[66:69], v[174:177], v[224:227], v[66:69]
	s_setprio 0
	s_barrier
	s_add_i32 s42, s45, s54
	v_lshl_add_u64 v[140:141], v[140:141], 0, s[84:85]
	s_mov_b32 m0, s42
	ds_read_b128 v[178:181], v145 offset:49152
	ds_read_b128 v[182:185], v145 offset:50176
	ds_read_b128 v[186:189], v145 offset:51200
	ds_read_b128 v[190:193], v145 offset:52224
	ds_read_b128 v[202:205], v145 offset:53248
	ds_read_b128 v[206:209], v145 offset:54272
	ds_read_b128 v[220:223], v145 offset:55296
	ds_read_b128 v[224:227], v145 offset:56320
	global_load_lds_dwordx4 v[140:141], off
	v_lshl_add_u64 v[140:141], v[194:195], 0, s[84:85]
	s_add_i32 m0, s42, 0x2000
	s_add_i32 s42, s73, s54
	global_load_lds_dwordx4 v[140:141], off
	v_lshl_add_u64 v[140:141], v[198:199], 0, s[84:85]
	s_mov_b32 m0, s42
	s_nop 0
	global_load_lds_dwordx4 v[140:141], off
	v_lshl_add_u64 v[140:141], v[200:201], 0, s[84:85]
	s_add_i32 m0, s42, 0x2000
	s_nop 0
	global_load_lds_dwordx4 v[140:141], off
	v_lshl_add_u64 v[140:141], v[210:211], 0, s[84:85]
	s_mov_b32 m0, s64
	s_nop 0
	global_load_lds_dwordx4 v[140:141], off
	v_lshl_add_u64 v[140:141], v[212:213], 0, s[84:85]
	s_mov_b32 m0, s65
	s_nop 0
	global_load_lds_dwordx4 v[140:141], off
	s_waitcnt vmcnt(8)
	s_waitcnt lgkmcnt(0)
	s_setprio 1
	s_barrier
	v_mfma_f32_16x16x32_bf16 v[62:65], v[146:149], v[178:181], v[62:65]
	v_mfma_f32_16x16x32_bf16 v[58:61], v[154:157], v[178:181], v[58:61]
	v_mfma_f32_16x16x32_bf16 v[54:57], v[146:149], v[186:189], v[54:57]
	v_mfma_f32_16x16x32_bf16 v[46:49], v[154:157], v[186:189], v[46:49]
	v_mfma_f32_16x16x32_bf16 v[38:41], v[146:149], v[202:205], v[38:41]
	v_mfma_f32_16x16x32_bf16 v[30:33], v[154:157], v[202:205], v[30:33]
	v_mfma_f32_16x16x32_bf16 v[22:25], v[146:149], v[220:223], v[22:25]
	v_mfma_f32_16x16x32_bf16 v[14:17], v[154:157], v[220:223], v[14:17]
	v_mfma_f32_16x16x32_bf16 v[62:65], v[150:153], v[182:185], v[62:65]
	v_mfma_f32_16x16x32_bf16 v[58:61], v[158:161], v[182:185], v[58:61]
	v_mfma_f32_16x16x32_bf16 v[54:57], v[150:153], v[190:193], v[54:57]
	v_mfma_f32_16x16x32_bf16 v[46:49], v[158:161], v[190:193], v[46:49]
	v_mfma_f32_16x16x32_bf16 v[38:41], v[150:153], v[206:209], v[38:41]
	v_mfma_f32_16x16x32_bf16 v[30:33], v[158:161], v[206:209], v[30:33]
	v_mfma_f32_16x16x32_bf16 v[22:25], v[150:153], v[224:227], v[22:25]
	v_mfma_f32_16x16x32_bf16 v[14:17], v[158:161], v[224:227], v[14:17]
	v_mfma_f32_16x16x32_bf16 v[50:53], v[162:165], v[178:181], v[50:53]
	v_mfma_f32_16x16x32_bf16 v[42:45], v[170:173], v[178:181], v[42:45]
	v_mfma_f32_16x16x32_bf16 v[34:37], v[162:165], v[186:189], v[34:37]
	v_mfma_f32_16x16x32_bf16 v[26:29], v[170:173], v[186:189], v[26:29]
	v_mfma_f32_16x16x32_bf16 v[18:21], v[162:165], v[202:205], v[18:21]
	v_mfma_f32_16x16x32_bf16 v[10:13], v[170:173], v[202:205], v[10:13]
	v_mfma_f32_16x16x32_bf16 v[6:9], v[162:165], v[220:223], v[6:9]
	v_mfma_f32_16x16x32_bf16 v[2:5], v[170:173], v[220:223], v[2:5]
	v_mfma_f32_16x16x32_bf16 v[50:53], v[166:169], v[182:185], v[50:53]
	v_mfma_f32_16x16x32_bf16 v[42:45], v[174:177], v[182:185], v[42:45]
	v_mfma_f32_16x16x32_bf16 v[34:37], v[166:169], v[190:193], v[34:37]
	v_mfma_f32_16x16x32_bf16 v[26:29], v[174:177], v[190:193], v[26:29]
	v_mfma_f32_16x16x32_bf16 v[18:21], v[166:169], v[206:209], v[18:21]
	v_mfma_f32_16x16x32_bf16 v[10:13], v[174:177], v[206:209], v[10:13]
	v_mfma_f32_16x16x32_bf16 v[6:9], v[166:169], v[224:227], v[6:9]
	v_mfma_f32_16x16x32_bf16 v[2:5], v[174:177], v[224:227], v[2:5]
	s_setprio 0
	s_barrier
	s_add_u32 vcc_lo, vcc_lo, 0x100
	s_addc_u32 vcc_hi, vcc_hi, 0
	s_add_u32 s82, s82, 0x100
	s_addc_u32 s83, s83, 0
	s_cmp_ge_u32 s72, s66
	s_mov_b32 s42, s72
	s_cbranch_scc0 .LBB0_308

.LBB0_351:
	s_add_u32 s8, s76, 0x80
	s_addc_u32 s9, s77, 0
	s_add_u32 s59, s36, 0x100
	s_addc_u32 s60, s37, 0
	s_mov_b32 s36, 0
	s_add_i32 s61, s36, 2
	s_add_u32 s45, s8, 0x80
	s_addc_u32 s37, s9, 0
	s_add_i32 s64, 0, 0x10000
	s_cmp_eq_u32 s48, s36
	s_cselect_b32 s37, s39, s37
	s_cselect_b32 s36, s38, s45
	s_cselect_b32 s63, s41, s60
	s_cselect_b32 s62, s40, s59
	s_add_i32 s45, 0, 0x14000
	v_add_u32_e32 v158, s64, v148
	v_add_u32_e32 v174, s45, v148
	ds_read_b128 v[144:147], v158
	ds_read_b128 v[150:153], v158 offset:1024
	ds_read_b128 v[154:157], v158 offset:2048
	ds_read_b128 v[158:161], v158 offset:3072
	ds_read_b128 v[162:165], v174
	ds_read_b128 v[166:169], v174 offset:1024
	ds_read_b128 v[170:173], v174 offset:2048
	ds_read_b128 v[174:177], v174 offset:3072
	v_lshl_add_u64 v[194:195], s[8:9], 0, v[140:141]
	s_add_i32 m0, s82, 0xc000
	ds_read_b128 v[178:181], v149
	ds_read_b128 v[182:185], v149 offset:1024
	ds_read_b128 v[186:189], v149 offset:2048
	ds_read_b128 v[190:193], v149 offset:3072
	ds_read_b128 v[202:205], v149 offset:4096
	ds_read_b128 v[206:209], v149 offset:5120
	ds_read_b128 v[220:223], v149 offset:6144
	ds_read_b128 v[224:227], v149 offset:7168
	global_load_lds_dwordx4 v[194:195], off
	v_lshl_add_u64 v[194:195], s[8:9], 0, v[142:143]
	s_add_i32 m0, s82, 0xe000
	s_nop 0
	global_load_lds_dwordx4 v[194:195], off
	s_waitcnt vmcnt(8)
	s_waitcnt lgkmcnt(0)
	s_setprio 1
	s_barrier
	v_mfma_f32_16x16x32_bf16 v[126:129], v[144:147], v[178:181], 0
	v_mfma_f32_16x16x32_bf16 v[122:125], v[154:157], v[178:181], 0
	v_mfma_f32_16x16x32_bf16 v[110:113], v[144:147], v[186:189], 0
	v_mfma_f32_16x16x32_bf16 v[106:109], v[154:157], v[186:189], 0
	v_mfma_f32_16x16x32_bf16 v[94:97], v[144:147], v[202:205], 0
	v_mfma_f32_16x16x32_bf16 v[90:93], v[154:157], v[202:205], 0
	v_mfma_f32_16x16x32_bf16 v[78:81], v[144:147], v[220:223], 0
	v_mfma_f32_16x16x32_bf16 v[74:77], v[154:157], v[220:223], 0
	v_mfma_f32_16x16x32_bf16 v[126:129], v[150:153], v[182:185], v[126:129]
	v_mfma_f32_16x16x32_bf16 v[122:125], v[158:161], v[182:185], v[122:125]
	v_mfma_f32_16x16x32_bf16 v[110:113], v[150:153], v[190:193], v[110:113]
	v_mfma_f32_16x16x32_bf16 v[106:109], v[158:161], v[190:193], v[106:109]
	v_mfma_f32_16x16x32_bf16 v[94:97], v[150:153], v[206:209], v[94:97]
	v_mfma_f32_16x16x32_bf16 v[90:93], v[158:161], v[206:209], v[90:93]
	v_mfma_f32_16x16x32_bf16 v[78:81], v[150:153], v[224:227], v[78:81]
	v_mfma_f32_16x16x32_bf16 v[74:77], v[158:161], v[224:227], v[74:77]
	v_mfma_f32_16x16x32_bf16 v[118:121], v[162:165], v[178:181], 0
	v_mfma_f32_16x16x32_bf16 v[114:117], v[170:173], v[178:181], 0
	v_mfma_f32_16x16x32_bf16 v[102:105], v[162:165], v[186:189], 0
	v_mfma_f32_16x16x32_bf16 v[98:101], v[170:173], v[186:189], 0
	v_mfma_f32_16x16x32_bf16 v[86:89], v[162:165], v[202:205], 0
	v_mfma_f32_16x16x32_bf16 v[82:85], v[170:173], v[202:205], 0
	v_mfma_f32_16x16x32_bf16 v[70:73], v[162:165], v[220:223], 0
	v_mfma_f32_16x16x32_bf16 v[66:69], v[170:173], v[220:223], 0
	v_mfma_f32_16x16x32_bf16 v[118:121], v[166:169], v[182:185], v[118:121]
	v_mfma_f32_16x16x32_bf16 v[114:117], v[174:177], v[182:185], v[114:117]
	v_mfma_f32_16x16x32_bf16 v[102:105], v[166:169], v[190:193], v[102:105]
	v_mfma_f32_16x16x32_bf16 v[98:101], v[174:177], v[190:193], v[98:101]
	v_mfma_f32_16x16x32_bf16 v[86:89], v[166:169], v[206:209], v[86:89]
	v_mfma_f32_16x16x32_bf16 v[82:85], v[174:177], v[206:209], v[82:85]
	v_mfma_f32_16x16x32_bf16 v[70:73], v[166:169], v[224:227], v[70:73]
	v_mfma_f32_16x16x32_bf16 v[66:69], v[174:177], v[224:227], v[66:69]
	s_setprio 0
	s_barrier
	s_add_i32 s64, s64, s79
	v_lshl_add_u64 v[194:195], s[62:63], 0, v[132:133]
	s_mov_b32 m0, s64
	ds_read_b128 v[178:181], v149 offset:16384
	ds_read_b128 v[182:185], v149 offset:17408
	ds_read_b128 v[186:189], v149 offset:18432
	ds_read_b128 v[190:193], v149 offset:19456
	ds_read_b128 v[202:205], v149 offset:20480
	ds_read_b128 v[206:209], v149 offset:21504
	ds_read_b128 v[220:223], v149 offset:22528
	ds_read_b128 v[224:227], v149 offset:23552
	global_load_lds_dwordx4 v[194:195], off
	s_add_i32 m0, s64, 0x2000
	v_lshl_add_u64 v[198:199], s[62:63], 0, v[136:137]
	s_add_u32 s62, s62, s80
	s_addc_u32 s63, s63, 0
	s_add_i32 s45, s45, s79
	global_load_lds_dwordx4 v[198:199], off
	v_lshl_add_u64 v[200:201], s[62:63], 0, v[132:133]
	s_mov_b32 m0, s45
	v_lshl_add_u64 v[210:211], s[62:63], 0, v[136:137]
	global_load_lds_dwordx4 v[200:201], off
	s_add_i32 m0, s45, 0x2000
	v_lshl_add_u64 v[212:213], s[36:37], 0, v[130:131]
	global_load_lds_dwordx4 v[210:211], off
	s_mov_b32 m0, s82
	v_lshl_add_u64 v[214:215], s[36:37], 0, v[134:135]
	global_load_lds_dwordx4 v[212:213], off
	s_mov_b32 m0, s83
	s_nop 0
	global_load_lds_dwordx4 v[214:215], off
	s_waitcnt vmcnt(8)
	s_waitcnt lgkmcnt(0)
	s_setprio 1
	s_barrier
	v_mfma_f32_16x16x32_bf16 v[62:65], v[144:147], v[178:181], 0
	v_mfma_f32_16x16x32_bf16 v[58:61], v[154:157], v[178:181], 0
	v_mfma_f32_16x16x32_bf16 v[46:49], v[144:147], v[186:189], 0
	v_mfma_f32_16x16x32_bf16 v[42:45], v[154:157], v[186:189], 0
	v_mfma_f32_16x16x32_bf16 v[30:33], v[144:147], v[202:205], 0
	v_mfma_f32_16x16x32_bf16 v[26:29], v[154:157], v[202:205], 0
	v_mfma_f32_16x16x32_bf16 v[14:17], v[144:147], v[220:223], 0
	v_mfma_f32_16x16x32_bf16 v[10:13], v[154:157], v[220:223], 0
	v_mfma_f32_16x16x32_bf16 v[62:65], v[150:153], v[182:185], v[62:65]
	v_mfma_f32_16x16x32_bf16 v[58:61], v[158:161], v[182:185], v[58:61]
	v_mfma_f32_16x16x32_bf16 v[46:49], v[150:153], v[190:193], v[46:49]
	v_mfma_f32_16x16x32_bf16 v[42:45], v[158:161], v[190:193], v[42:45]
	v_mfma_f32_16x16x32_bf16 v[30:33], v[150:153], v[206:209], v[30:33]
	v_mfma_f32_16x16x32_bf16 v[26:29], v[158:161], v[206:209], v[26:29]
	v_mfma_f32_16x16x32_bf16 v[14:17], v[150:153], v[224:227], v[14:17]
	v_mfma_f32_16x16x32_bf16 v[10:13], v[158:161], v[224:227], v[10:13]
	v_mfma_f32_16x16x32_bf16 v[54:57], v[162:165], v[178:181], 0
	v_mfma_f32_16x16x32_bf16 v[50:53], v[170:173], v[178:181], 0
	v_mfma_f32_16x16x32_bf16 v[38:41], v[162:165], v[186:189], 0
	v_mfma_f32_16x16x32_bf16 v[34:37], v[170:173], v[186:189], 0
	v_mfma_f32_16x16x32_bf16 v[22:25], v[162:165], v[202:205], 0
	v_mfma_f32_16x16x32_bf16 v[18:21], v[170:173], v[202:205], 0
	v_mfma_f32_16x16x32_bf16 v[6:9], v[162:165], v[220:223], 0
	v_mfma_f32_16x16x32_bf16 v[2:5], v[170:173], v[220:223], 0
	v_mfma_f32_16x16x32_bf16 v[54:57], v[166:169], v[182:185], v[54:57]
	v_mfma_f32_16x16x32_bf16 v[50:53], v[174:177], v[182:185], v[50:53]
	v_mfma_f32_16x16x32_bf16 v[38:41], v[166:169], v[190:193], v[38:41]
	v_mfma_f32_16x16x32_bf16 v[34:37], v[174:177], v[190:193], v[34:37]
	v_mfma_f32_16x16x32_bf16 v[22:25], v[166:169], v[206:209], v[22:25]
	v_mfma_f32_16x16x32_bf16 v[18:21], v[174:177], v[206:209], v[18:21]
	v_mfma_f32_16x16x32_bf16 v[6:9], v[166:169], v[224:227], v[6:9]
	v_mfma_f32_16x16x32_bf16 v[2:5], v[174:177], v[224:227], v[2:5]
	s_setprio 0
	s_barrier
	s_add_i32 s45, 0, 0x18000
	s_add_i32 s62, 0, 0x1c000
	v_add_u32_e32 v158, s45, v148
	v_add_u32_e32 v174, s62, v148
	ds_read_b128 v[144:147], v158
	ds_read_b128 v[150:153], v158 offset:1024
	ds_read_b128 v[154:157], v158 offset:2048
	ds_read_b128 v[158:161], v158 offset:3072
	ds_read_b128 v[162:165], v174
	ds_read_b128 v[166:169], v174 offset:1024
	ds_read_b128 v[170:173], v174 offset:2048
	ds_read_b128 v[174:177], v174 offset:3072
	s_add_u32 s36, s36, s80
	s_addc_u32 s37, s37, 0
	s_mov_b32 m0, s86
	v_lshl_add_u64 v[216:217], s[36:37], 0, v[130:131]
	ds_read_b128 v[178:181], v149 offset:32768
	ds_read_b128 v[182:185], v149 offset:33792
	ds_read_b128 v[186:189], v149 offset:34816
	ds_read_b128 v[190:193], v149 offset:35840
	ds_read_b128 v[202:205], v149 offset:36864
	ds_read_b128 v[206:209], v149 offset:37888
	ds_read_b128 v[220:223], v149 offset:38912
	ds_read_b128 v[224:227], v149 offset:39936
	global_load_lds_dwordx4 v[216:217], off
	v_lshl_add_u64 v[216:217], s[36:37], 0, v[134:135]
	s_mov_b32 m0, s87
	s_nop 0
	global_load_lds_dwordx4 v[216:217], off
	s_waitcnt vmcnt(8)
	s_waitcnt lgkmcnt(0)
	s_setprio 1
	s_barrier
	v_mfma_f32_16x16x32_bf16 v[126:129], v[144:147], v[178:181], v[126:129]
	v_mfma_f32_16x16x32_bf16 v[122:125], v[154:157], v[178:181], v[122:125]
	v_mfma_f32_16x16x32_bf16 v[110:113], v[144:147], v[186:189], v[110:113]
	v_mfma_f32_16x16x32_bf16 v[106:109], v[154:157], v[186:189], v[106:109]
	v_mfma_f32_16x16x32_bf16 v[94:97], v[144:147], v[202:205], v[94:97]
	v_mfma_f32_16x16x32_bf16 v[90:93], v[154:157], v[202:205], v[90:93]
	v_mfma_f32_16x16x32_bf16 v[78:81], v[144:147], v[220:223], v[78:81]
	v_mfma_f32_16x16x32_bf16 v[74:77], v[154:157], v[220:223], v[74:77]
	v_mfma_f32_16x16x32_bf16 v[126:129], v[150:153], v[182:185], v[126:129]
	v_mfma_f32_16x16x32_bf16 v[122:125], v[158:161], v[182:185], v[122:125]
	v_mfma_f32_16x16x32_bf16 v[110:113], v[150:153], v[190:193], v[110:113]
	v_mfma_f32_16x16x32_bf16 v[106:109], v[158:161], v[190:193], v[106:109]
	v_mfma_f32_16x16x32_bf16 v[94:97], v[150:153], v[206:209], v[94:97]
	v_mfma_f32_16x16x32_bf16 v[90:93], v[158:161], v[206:209], v[90:93]
	v_mfma_f32_16x16x32_bf16 v[78:81], v[150:153], v[224:227], v[78:81]
	v_mfma_f32_16x16x32_bf16 v[74:77], v[158:161], v[224:227], v[74:77]
	v_mfma_f32_16x16x32_bf16 v[118:121], v[162:165], v[178:181], v[118:121]
	v_mfma_f32_16x16x32_bf16 v[114:117], v[170:173], v[178:181], v[114:117]
	v_mfma_f32_16x16x32_bf16 v[102:105], v[162:165], v[186:189], v[102:105]
	v_mfma_f32_16x16x32_bf16 v[98:101], v[170:173], v[186:189], v[98:101]
	v_mfma_f32_16x16x32_bf16 v[86:89], v[162:165], v[202:205], v[86:89]
	v_mfma_f32_16x16x32_bf16 v[82:85], v[170:173], v[202:205], v[82:85]
	v_mfma_f32_16x16x32_bf16 v[70:73], v[162:165], v[220:223], v[70:73]
	v_mfma_f32_16x16x32_bf16 v[66:69], v[170:173], v[220:223], v[66:69]
	v_mfma_f32_16x16x32_bf16 v[118:121], v[166:169], v[182:185], v[118:121]
	v_mfma_f32_16x16x32_bf16 v[114:117], v[174:177], v[182:185], v[114:117]
	v_mfma_f32_16x16x32_bf16 v[102:105], v[166:169], v[190:193], v[102:105]
	v_mfma_f32_16x16x32_bf16 v[98:101], v[174:177], v[190:193], v[98:101]
	v_mfma_f32_16x16x32_bf16 v[86:89], v[166:169], v[206:209], v[86:89]
	v_mfma_f32_16x16x32_bf16 v[82:85], v[174:177], v[206:209], v[82:85]
	v_mfma_f32_16x16x32_bf16 v[70:73], v[166:169], v[224:227], v[70:73]
	v_mfma_f32_16x16x32_bf16 v[66:69], v[174:177], v[224:227], v[66:69]
	s_setprio 0
	s_barrier
	s_add_i32 s36, s45, s79
	v_lshl_add_u64 v[194:195], v[194:195], 0, s[84:85]
	s_mov_b32 m0, s36
	ds_read_b128 v[178:181], v149 offset:49152
	ds_read_b128 v[182:185], v149 offset:50176
	ds_read_b128 v[186:189], v149 offset:51200
	ds_read_b128 v[190:193], v149 offset:52224
	ds_read_b128 v[202:205], v149 offset:53248
	ds_read_b128 v[206:209], v149 offset:54272
	ds_read_b128 v[220:223], v149 offset:55296
	ds_read_b128 v[224:227], v149 offset:56320
	global_load_lds_dwordx4 v[194:195], off
	v_lshl_add_u64 v[194:195], v[198:199], 0, s[84:85]
	s_add_i32 m0, s36, 0x2000
	s_add_i32 s36, s62, s79
	global_load_lds_dwordx4 v[194:195], off
	v_lshl_add_u64 v[194:195], v[200:201], 0, s[84:85]
	s_mov_b32 m0, s36
	s_nop 0
	global_load_lds_dwordx4 v[194:195], off
	v_lshl_add_u64 v[194:195], v[210:211], 0, s[84:85]
	s_add_i32 m0, s36, 0x2000
	s_nop 0
	global_load_lds_dwordx4 v[194:195], off
	v_lshl_add_u64 v[194:195], v[212:213], 0, s[84:85]
	s_mov_b32 m0, s46
	s_nop 0
	global_load_lds_dwordx4 v[194:195], off
	v_lshl_add_u64 v[194:195], v[214:215], 0, s[84:85]
	s_mov_b32 m0, s47
	s_nop 0
	global_load_lds_dwordx4 v[194:195], off
	s_waitcnt vmcnt(8)
	s_waitcnt lgkmcnt(0)
	s_setprio 1
	s_barrier
	v_mfma_f32_16x16x32_bf16 v[62:65], v[144:147], v[178:181], v[62:65]
	v_mfma_f32_16x16x32_bf16 v[58:61], v[154:157], v[178:181], v[58:61]
	v_mfma_f32_16x16x32_bf16 v[46:49], v[144:147], v[186:189], v[46:49]
	v_mfma_f32_16x16x32_bf16 v[42:45], v[154:157], v[186:189], v[42:45]
	v_mfma_f32_16x16x32_bf16 v[30:33], v[144:147], v[202:205], v[30:33]
	v_mfma_f32_16x16x32_bf16 v[26:29], v[154:157], v[202:205], v[26:29]
	v_mfma_f32_16x16x32_bf16 v[14:17], v[144:147], v[220:223], v[14:17]
	v_mfma_f32_16x16x32_bf16 v[10:13], v[154:157], v[220:223], v[10:13]
	v_mfma_f32_16x16x32_bf16 v[62:65], v[150:153], v[182:185], v[62:65]
	v_mfma_f32_16x16x32_bf16 v[58:61], v[158:161], v[182:185], v[58:61]
	v_mfma_f32_16x16x32_bf16 v[46:49], v[150:153], v[190:193], v[46:49]
	v_mfma_f32_16x16x32_bf16 v[42:45], v[158:161], v[190:193], v[42:45]
	v_mfma_f32_16x16x32_bf16 v[30:33], v[150:153], v[206:209], v[30:33]
	v_mfma_f32_16x16x32_bf16 v[26:29], v[158:161], v[206:209], v[26:29]
	v_mfma_f32_16x16x32_bf16 v[14:17], v[150:153], v[224:227], v[14:17]
	v_mfma_f32_16x16x32_bf16 v[10:13], v[158:161], v[224:227], v[10:13]
	v_mfma_f32_16x16x32_bf16 v[54:57], v[162:165], v[178:181], v[54:57]
	v_mfma_f32_16x16x32_bf16 v[50:53], v[170:173], v[178:181], v[50:53]
	v_mfma_f32_16x16x32_bf16 v[38:41], v[162:165], v[186:189], v[38:41]
	v_mfma_f32_16x16x32_bf16 v[34:37], v[170:173], v[186:189], v[34:37]
	v_mfma_f32_16x16x32_bf16 v[22:25], v[162:165], v[202:205], v[22:25]
	v_mfma_f32_16x16x32_bf16 v[18:21], v[170:173], v[202:205], v[18:21]
	v_mfma_f32_16x16x32_bf16 v[6:9], v[162:165], v[220:223], v[6:9]
	v_mfma_f32_16x16x32_bf16 v[2:5], v[170:173], v[220:223], v[2:5]
	v_mfma_f32_16x16x32_bf16 v[54:57], v[166:169], v[182:185], v[54:57]
	v_mfma_f32_16x16x32_bf16 v[50:53], v[174:177], v[182:185], v[50:53]
	v_mfma_f32_16x16x32_bf16 v[38:41], v[166:169], v[190:193], v[38:41]
	v_mfma_f32_16x16x32_bf16 v[34:37], v[174:177], v[190:193], v[34:37]
	v_mfma_f32_16x16x32_bf16 v[22:25], v[166:169], v[206:209], v[22:25]
	v_mfma_f32_16x16x32_bf16 v[18:21], v[174:177], v[206:209], v[18:21]
	v_mfma_f32_16x16x32_bf16 v[6:9], v[166:169], v[224:227], v[6:9]
	v_mfma_f32_16x16x32_bf16 v[2:5], v[174:177], v[224:227], v[2:5]
	s_setprio 0
	s_barrier
	s_add_u32 s8, s8, 0x100
	s_addc_u32 s9, s9, 0
	s_add_u32 s59, s59, 0x100
	s_addc_u32 s60, s60, 0
	s_cmp_ge_u32 s61, s90
	s_mov_b32 s36, s61
	s_cbranch_scc1 .Lpeel_exit_vt
.LBB0_352:
	s_add_i32 s61, s36, 2
	s_add_u32 s45, s8, 0x80
	s_addc_u32 s37, s9, 0
	s_add_i32 s64, 0, 0x10000
	s_cmp_eq_u32 s48, s36
	s_cselect_b32 s37, s39, s37
	s_cselect_b32 s36, s38, s45
	s_cselect_b32 s63, s41, s60
	s_cselect_b32 s62, s40, s59
	s_add_i32 s45, 0, 0x14000
	v_add_u32_e32 v158, s64, v148
	v_add_u32_e32 v174, s45, v148
	ds_read_b128 v[144:147], v158
	ds_read_b128 v[150:153], v158 offset:1024
	ds_read_b128 v[154:157], v158 offset:2048
	ds_read_b128 v[158:161], v158 offset:3072
	ds_read_b128 v[162:165], v174
	ds_read_b128 v[166:169], v174 offset:1024
	ds_read_b128 v[170:173], v174 offset:2048
	ds_read_b128 v[174:177], v174 offset:3072
	v_lshl_add_u64 v[194:195], s[8:9], 0, v[140:141]
	s_add_i32 m0, s82, 0xc000
	ds_read_b128 v[178:181], v149
	ds_read_b128 v[182:185], v149 offset:1024
	ds_read_b128 v[186:189], v149 offset:2048
	ds_read_b128 v[190:193], v149 offset:3072
	ds_read_b128 v[202:205], v149 offset:4096
	ds_read_b128 v[206:209], v149 offset:5120
	ds_read_b128 v[220:223], v149 offset:6144
	ds_read_b128 v[224:227], v149 offset:7168
	global_load_lds_dwordx4 v[194:195], off
	v_lshl_add_u64 v[194:195], s[8:9], 0, v[142:143]
	s_add_i32 m0, s82, 0xe000
	s_nop 0
	global_load_lds_dwordx4 v[194:195], off
	s_waitcnt vmcnt(8)
	s_waitcnt lgkmcnt(0)
	s_setprio 1
	s_barrier
	v_mfma_f32_16x16x32_bf16 v[126:129], v[144:147], v[178:181], v[126:129]
	v_mfma_f32_16x16x32_bf16 v[122:125], v[154:157], v[178:181], v[122:125]
	v_mfma_f32_16x16x32_bf16 v[110:113], v[144:147], v[186:189], v[110:113]
	v_mfma_f32_16x16x32_bf16 v[106:109], v[154:157], v[186:189], v[106:109]
	v_mfma_f32_16x16x32_bf16 v[94:97], v[144:147], v[202:205], v[94:97]
	v_mfma_f32_16x16x32_bf16 v[90:93], v[154:157], v[202:205], v[90:93]
	v_mfma_f32_16x16x32_bf16 v[78:81], v[144:147], v[220:223], v[78:81]
	v_mfma_f32_16x16x32_bf16 v[74:77], v[154:157], v[220:223], v[74:77]
	v_mfma_f32_16x16x32_bf16 v[126:129], v[150:153], v[182:185], v[126:129]
	v_mfma_f32_16x16x32_bf16 v[122:125], v[158:161], v[182:185], v[122:125]
	v_mfma_f32_16x16x32_bf16 v[110:113], v[150:153], v[190:193], v[110:113]
	v_mfma_f32_16x16x32_bf16 v[106:109], v[158:161], v[190:193], v[106:109]
	v_mfma_f32_16x16x32_bf16 v[94:97], v[150:153], v[206:209], v[94:97]
	v_mfma_f32_16x16x32_bf16 v[90:93], v[158:161], v[206:209], v[90:93]
	v_mfma_f32_16x16x32_bf16 v[78:81], v[150:153], v[224:227], v[78:81]
	v_mfma_f32_16x16x32_bf16 v[74:77], v[158:161], v[224:227], v[74:77]
	v_mfma_f32_16x16x32_bf16 v[118:121], v[162:165], v[178:181], v[118:121]
	v_mfma_f32_16x16x32_bf16 v[114:117], v[170:173], v[178:181], v[114:117]
	v_mfma_f32_16x16x32_bf16 v[102:105], v[162:165], v[186:189], v[102:105]
	v_mfma_f32_16x16x32_bf16 v[98:101], v[170:173], v[186:189], v[98:101]
	v_mfma_f32_16x16x32_bf16 v[86:89], v[162:165], v[202:205], v[86:89]
	v_mfma_f32_16x16x32_bf16 v[82:85], v[170:173], v[202:205], v[82:85]
	v_mfma_f32_16x16x32_bf16 v[70:73], v[162:165], v[220:223], v[70:73]
	v_mfma_f32_16x16x32_bf16 v[66:69], v[170:173], v[220:223], v[66:69]
	v_mfma_f32_16x16x32_bf16 v[118:121], v[166:169], v[182:185], v[118:121]
	v_mfma_f32_16x16x32_bf16 v[114:117], v[174:177], v[182:185], v[114:117]
	v_mfma_f32_16x16x32_bf16 v[102:105], v[166:169], v[190:193], v[102:105]
	v_mfma_f32_16x16x32_bf16 v[98:101], v[174:177], v[190:193], v[98:101]
	v_mfma_f32_16x16x32_bf16 v[86:89], v[166:169], v[206:209], v[86:89]
	v_mfma_f32_16x16x32_bf16 v[82:85], v[174:177], v[206:209], v[82:85]
	v_mfma_f32_16x16x32_bf16 v[70:73], v[166:169], v[224:227], v[70:73]
	v_mfma_f32_16x16x32_bf16 v[66:69], v[174:177], v[224:227], v[66:69]
	s_setprio 0
	s_barrier
	s_add_i32 s64, s64, s79
	v_lshl_add_u64 v[194:195], s[62:63], 0, v[132:133]
	s_mov_b32 m0, s64
	ds_read_b128 v[178:181], v149 offset:16384
	ds_read_b128 v[182:185], v149 offset:17408
	ds_read_b128 v[186:189], v149 offset:18432
	ds_read_b128 v[190:193], v149 offset:19456
	ds_read_b128 v[202:205], v149 offset:20480
	ds_read_b128 v[206:209], v149 offset:21504
	ds_read_b128 v[220:223], v149 offset:22528
	ds_read_b128 v[224:227], v149 offset:23552
	global_load_lds_dwordx4 v[194:195], off
	s_add_i32 m0, s64, 0x2000
	v_lshl_add_u64 v[198:199], s[62:63], 0, v[136:137]
	s_add_u32 s62, s62, s80
	s_addc_u32 s63, s63, 0
	s_add_i32 s45, s45, s79
	global_load_lds_dwordx4 v[198:199], off
	v_lshl_add_u64 v[200:201], s[62:63], 0, v[132:133]
	s_mov_b32 m0, s45
	v_lshl_add_u64 v[210:211], s[62:63], 0, v[136:137]
	global_load_lds_dwordx4 v[200:201], off
	s_add_i32 m0, s45, 0x2000
	v_lshl_add_u64 v[212:213], s[36:37], 0, v[130:131]
	global_load_lds_dwordx4 v[210:211], off
	s_mov_b32 m0, s82
	v_lshl_add_u64 v[214:215], s[36:37], 0, v[134:135]
	global_load_lds_dwordx4 v[212:213], off
	s_mov_b32 m0, s83
	s_nop 0
	global_load_lds_dwordx4 v[214:215], off
	s_waitcnt vmcnt(8)
	s_waitcnt lgkmcnt(0)
	s_setprio 1
	s_barrier
	v_mfma_f32_16x16x32_bf16 v[62:65], v[144:147], v[178:181], v[62:65]
	v_mfma_f32_16x16x32_bf16 v[58:61], v[154:157], v[178:181], v[58:61]
	v_mfma_f32_16x16x32_bf16 v[46:49], v[144:147], v[186:189], v[46:49]
	v_mfma_f32_16x16x32_bf16 v[42:45], v[154:157], v[186:189], v[42:45]
	v_mfma_f32_16x16x32_bf16 v[30:33], v[144:147], v[202:205], v[30:33]
	v_mfma_f32_16x16x32_bf16 v[26:29], v[154:157], v[202:205], v[26:29]
	v_mfma_f32_16x16x32_bf16 v[14:17], v[144:147], v[220:223], v[14:17]
	v_mfma_f32_16x16x32_bf16 v[10:13], v[154:157], v[220:223], v[10:13]
	v_mfma_f32_16x16x32_bf16 v[62:65], v[150:153], v[182:185], v[62:65]
	v_mfma_f32_16x16x32_bf16 v[58:61], v[158:161], v[182:185], v[58:61]
	v_mfma_f32_16x16x32_bf16 v[46:49], v[150:153], v[190:193], v[46:49]
	v_mfma_f32_16x16x32_bf16 v[42:45], v[158:161], v[190:193], v[42:45]
	v_mfma_f32_16x16x32_bf16 v[30:33], v[150:153], v[206:209], v[30:33]
	v_mfma_f32_16x16x32_bf16 v[26:29], v[158:161], v[206:209], v[26:29]
	v_mfma_f32_16x16x32_bf16 v[14:17], v[150:153], v[224:227], v[14:17]
	v_mfma_f32_16x16x32_bf16 v[10:13], v[158:161], v[224:227], v[10:13]
	v_mfma_f32_16x16x32_bf16 v[54:57], v[162:165], v[178:181], v[54:57]
	v_mfma_f32_16x16x32_bf16 v[50:53], v[170:173], v[178:181], v[50:53]
	v_mfma_f32_16x16x32_bf16 v[38:41], v[162:165], v[186:189], v[38:41]
	v_mfma_f32_16x16x32_bf16 v[34:37], v[170:173], v[186:189], v[34:37]
	v_mfma_f32_16x16x32_bf16 v[22:25], v[162:165], v[202:205], v[22:25]
	v_mfma_f32_16x16x32_bf16 v[18:21], v[170:173], v[202:205], v[18:21]
	v_mfma_f32_16x16x32_bf16 v[6:9], v[162:165], v[220:223], v[6:9]
	v_mfma_f32_16x16x32_bf16 v[2:5], v[170:173], v[220:223], v[2:5]
	v_mfma_f32_16x16x32_bf16 v[54:57], v[166:169], v[182:185], v[54:57]
	v_mfma_f32_16x16x32_bf16 v[50:53], v[174:177], v[182:185], v[50:53]
	v_mfma_f32_16x16x32_bf16 v[38:41], v[166:169], v[190:193], v[38:41]
	v_mfma_f32_16x16x32_bf16 v[34:37], v[174:177], v[190:193], v[34:37]
	v_mfma_f32_16x16x32_bf16 v[22:25], v[166:169], v[206:209], v[22:25]
	v_mfma_f32_16x16x32_bf16 v[18:21], v[174:177], v[206:209], v[18:21]
	v_mfma_f32_16x16x32_bf16 v[6:9], v[166:169], v[224:227], v[6:9]
	v_mfma_f32_16x16x32_bf16 v[2:5], v[174:177], v[224:227], v[2:5]
	s_setprio 0
	s_barrier
	s_add_i32 s45, 0, 0x18000
	s_add_i32 s62, 0, 0x1c000
	v_add_u32_e32 v158, s45, v148
	v_add_u32_e32 v174, s62, v148
	ds_read_b128 v[144:147], v158
	ds_read_b128 v[150:153], v158 offset:1024
	ds_read_b128 v[154:157], v158 offset:2048
	ds_read_b128 v[158:161], v158 offset:3072
	ds_read_b128 v[162:165], v174
	ds_read_b128 v[166:169], v174 offset:1024
	ds_read_b128 v[170:173], v174 offset:2048
	ds_read_b128 v[174:177], v174 offset:3072
	s_add_u32 s36, s36, s80
	s_addc_u32 s37, s37, 0
	s_mov_b32 m0, s86
	v_lshl_add_u64 v[216:217], s[36:37], 0, v[130:131]
	ds_read_b128 v[178:181], v149 offset:32768
	ds_read_b128 v[182:185], v149 offset:33792
	ds_read_b128 v[186:189], v149 offset:34816
	ds_read_b128 v[190:193], v149 offset:35840
	ds_read_b128 v[202:205], v149 offset:36864
	ds_read_b128 v[206:209], v149 offset:37888
	ds_read_b128 v[220:223], v149 offset:38912
	ds_read_b128 v[224:227], v149 offset:39936
	global_load_lds_dwordx4 v[216:217], off
	v_lshl_add_u64 v[216:217], s[36:37], 0, v[134:135]
	s_mov_b32 m0, s87
	s_nop 0
	global_load_lds_dwordx4 v[216:217], off
	s_waitcnt vmcnt(8)
	s_waitcnt lgkmcnt(0)
	s_setprio 1
	s_barrier
	v_mfma_f32_16x16x32_bf16 v[126:129], v[144:147], v[178:181], v[126:129]
	v_mfma_f32_16x16x32_bf16 v[122:125], v[154:157], v[178:181], v[122:125]
	v_mfma_f32_16x16x32_bf16 v[110:113], v[144:147], v[186:189], v[110:113]
	v_mfma_f32_16x16x32_bf16 v[106:109], v[154:157], v[186:189], v[106:109]
	v_mfma_f32_16x16x32_bf16 v[94:97], v[144:147], v[202:205], v[94:97]
	v_mfma_f32_16x16x32_bf16 v[90:93], v[154:157], v[202:205], v[90:93]
	v_mfma_f32_16x16x32_bf16 v[78:81], v[144:147], v[220:223], v[78:81]
	v_mfma_f32_16x16x32_bf16 v[74:77], v[154:157], v[220:223], v[74:77]
	v_mfma_f32_16x16x32_bf16 v[126:129], v[150:153], v[182:185], v[126:129]
	v_mfma_f32_16x16x32_bf16 v[122:125], v[158:161], v[182:185], v[122:125]
	v_mfma_f32_16x16x32_bf16 v[110:113], v[150:153], v[190:193], v[110:113]
	v_mfma_f32_16x16x32_bf16 v[106:109], v[158:161], v[190:193], v[106:109]
	v_mfma_f32_16x16x32_bf16 v[94:97], v[150:153], v[206:209], v[94:97]
	v_mfma_f32_16x16x32_bf16 v[90:93], v[158:161], v[206:209], v[90:93]
	v_mfma_f32_16x16x32_bf16 v[78:81], v[150:153], v[224:227], v[78:81]
	v_mfma_f32_16x16x32_bf16 v[74:77], v[158:161], v[224:227], v[74:77]
	v_mfma_f32_16x16x32_bf16 v[118:121], v[162:165], v[178:181], v[118:121]
	v_mfma_f32_16x16x32_bf16 v[114:117], v[170:173], v[178:181], v[114:117]
	v_mfma_f32_16x16x32_bf16 v[102:105], v[162:165], v[186:189], v[102:105]
	v_mfma_f32_16x16x32_bf16 v[98:101], v[170:173], v[186:189], v[98:101]
	v_mfma_f32_16x16x32_bf16 v[86:89], v[162:165], v[202:205], v[86:89]
	v_mfma_f32_16x16x32_bf16 v[82:85], v[170:173], v[202:205], v[82:85]
	v_mfma_f32_16x16x32_bf16 v[70:73], v[162:165], v[220:223], v[70:73]
	v_mfma_f32_16x16x32_bf16 v[66:69], v[170:173], v[220:223], v[66:69]
	v_mfma_f32_16x16x32_bf16 v[118:121], v[166:169], v[182:185], v[118:121]
	v_mfma_f32_16x16x32_bf16 v[114:117], v[174:177], v[182:185], v[114:117]
	v_mfma_f32_16x16x32_bf16 v[102:105], v[166:169], v[190:193], v[102:105]
	v_mfma_f32_16x16x32_bf16 v[98:101], v[174:177], v[190:193], v[98:101]
	v_mfma_f32_16x16x32_bf16 v[86:89], v[166:169], v[206:209], v[86:89]
	v_mfma_f32_16x16x32_bf16 v[82:85], v[174:177], v[206:209], v[82:85]
	v_mfma_f32_16x16x32_bf16 v[70:73], v[166:169], v[224:227], v[70:73]
	v_mfma_f32_16x16x32_bf16 v[66:69], v[174:177], v[224:227], v[66:69]
	s_setprio 0
	s_barrier
	s_add_i32 s36, s45, s79
	v_lshl_add_u64 v[194:195], v[194:195], 0, s[84:85]
	s_mov_b32 m0, s36
	ds_read_b128 v[178:181], v149 offset:49152
	ds_read_b128 v[182:185], v149 offset:50176
	ds_read_b128 v[186:189], v149 offset:51200
	ds_read_b128 v[190:193], v149 offset:52224
	ds_read_b128 v[202:205], v149 offset:53248
	ds_read_b128 v[206:209], v149 offset:54272
	ds_read_b128 v[220:223], v149 offset:55296
	ds_read_b128 v[224:227], v149 offset:56320
	global_load_lds_dwordx4 v[194:195], off
	v_lshl_add_u64 v[194:195], v[198:199], 0, s[84:85]
	s_add_i32 m0, s36, 0x2000
	s_add_i32 s36, s62, s79
	global_load_lds_dwordx4 v[194:195], off
	v_lshl_add_u64 v[194:195], v[200:201], 0, s[84:85]
	s_mov_b32 m0, s36
	s_nop 0
	global_load_lds_dwordx4 v[194:195], off
	v_lshl_add_u64 v[194:195], v[210:211], 0, s[84:85]
	s_add_i32 m0, s36, 0x2000
	s_nop 0
	global_load_lds_dwordx4 v[194:195], off
	v_lshl_add_u64 v[194:195], v[212:213], 0, s[84:85]
	s_mov_b32 m0, s46
	s_nop 0
	global_load_lds_dwordx4 v[194:195], off
	v_lshl_add_u64 v[194:195], v[214:215], 0, s[84:85]
	s_mov_b32 m0, s47
	s_nop 0
	global_load_lds_dwordx4 v[194:195], off
	s_waitcnt vmcnt(8)
	s_waitcnt lgkmcnt(0)
	s_setprio 1
	s_barrier
	v_mfma_f32_16x16x32_bf16 v[62:65], v[144:147], v[178:181], v[62:65]
	v_mfma_f32_16x16x32_bf16 v[58:61], v[154:157], v[178:181], v[58:61]
	v_mfma_f32_16x16x32_bf16 v[46:49], v[144:147], v[186:189], v[46:49]
	v_mfma_f32_16x16x32_bf16 v[42:45], v[154:157], v[186:189], v[42:45]
	v_mfma_f32_16x16x32_bf16 v[30:33], v[144:147], v[202:205], v[30:33]
	v_mfma_f32_16x16x32_bf16 v[26:29], v[154:157], v[202:205], v[26:29]
	v_mfma_f32_16x16x32_bf16 v[14:17], v[144:147], v[220:223], v[14:17]
	v_mfma_f32_16x16x32_bf16 v[10:13], v[154:157], v[220:223], v[10:13]
	v_mfma_f32_16x16x32_bf16 v[62:65], v[150:153], v[182:185], v[62:65]
	v_mfma_f32_16x16x32_bf16 v[58:61], v[158:161], v[182:185], v[58:61]
	v_mfma_f32_16x16x32_bf16 v[46:49], v[150:153], v[190:193], v[46:49]
	v_mfma_f32_16x16x32_bf16 v[42:45], v[158:161], v[190:193], v[42:45]
	v_mfma_f32_16x16x32_bf16 v[30:33], v[150:153], v[206:209], v[30:33]
	v_mfma_f32_16x16x32_bf16 v[26:29], v[158:161], v[206:209], v[26:29]
	v_mfma_f32_16x16x32_bf16 v[14:17], v[150:153], v[224:227], v[14:17]
	v_mfma_f32_16x16x32_bf16 v[10:13], v[158:161], v[224:227], v[10:13]
	v_mfma_f32_16x16x32_bf16 v[54:57], v[162:165], v[178:181], v[54:57]
	v_mfma_f32_16x16x32_bf16 v[50:53], v[170:173], v[178:181], v[50:53]
	v_mfma_f32_16x16x32_bf16 v[38:41], v[162:165], v[186:189], v[38:41]
	v_mfma_f32_16x16x32_bf16 v[34:37], v[170:173], v[186:189], v[34:37]
	v_mfma_f32_16x16x32_bf16 v[22:25], v[162:165], v[202:205], v[22:25]
	v_mfma_f32_16x16x32_bf16 v[18:21], v[170:173], v[202:205], v[18:21]
	v_mfma_f32_16x16x32_bf16 v[6:9], v[162:165], v[220:223], v[6:9]
	v_mfma_f32_16x16x32_bf16 v[2:5], v[170:173], v[220:223], v[2:5]
	v_mfma_f32_16x16x32_bf16 v[54:57], v[166:169], v[182:185], v[54:57]
	v_mfma_f32_16x16x32_bf16 v[50:53], v[174:177], v[182:185], v[50:53]
	v_mfma_f32_16x16x32_bf16 v[38:41], v[166:169], v[190:193], v[38:41]
	v_mfma_f32_16x16x32_bf16 v[34:37], v[174:177], v[190:193], v[34:37]
	v_mfma_f32_16x16x32_bf16 v[22:25], v[166:169], v[206:209], v[22:25]
	v_mfma_f32_16x16x32_bf16 v[18:21], v[174:177], v[206:209], v[18:21]
	v_mfma_f32_16x16x32_bf16 v[6:9], v[166:169], v[224:227], v[6:9]
	v_mfma_f32_16x16x32_bf16 v[2:5], v[174:177], v[224:227], v[2:5]
	s_setprio 0
	s_barrier
	s_add_u32 s8, s8, 0x100
	s_addc_u32 s9, s9, 0
	s_add_u32 s59, s59, 0x100
	s_addc_u32 s60, s60, 0
	s_cmp_ge_u32 s61, s90
	s_mov_b32 s36, s61
	s_cbranch_scc0 .LBB0_352

.LBB0_438:
	s_add_i32 s58, s36, 2
	s_add_u32 s59, s34, 0x80
	s_addc_u32 s37, s35, 0
	s_add_i32 s62, 0, 0x10000
	s_cmp_eq_u32 s50, s36
	s_cselect_b32 s37, s9, s37
	s_cselect_b32 s36, s8, s59
	v_add_u32_e32 v144, s62, v147
	s_cselect_b32 s61, s21, s57
	s_cselect_b32 s60, s20, s56
	s_add_i32 s59, 0, 0x14000
	ds_read_b128 v[136:139], v144
	ds_read_b128 v[140:143], v144 offset:1024
	ds_read_b128 v[150:153], v144 offset:2048
	ds_read_b128 v[154:157], v144 offset:3072
	v_add_u32_e32 v144, s59, v147
	ds_read_b128 v[158:161], v144
	ds_read_b128 v[162:165], v144 offset:1024
	ds_read_b128 v[166:169], v144 offset:2048
	ds_read_b128 v[170:173], v144 offset:3072
	v_lshl_add_u64 v[144:145], s[34:35], 0, v[132:133]
	s_add_i32 m0, s79, 0xc000
	ds_read_b128 v[174:177], v149
	ds_read_b128 v[178:181], v149 offset:1024
	ds_read_b128 v[182:185], v149 offset:2048
	ds_read_b128 v[186:189], v149 offset:3072
	ds_read_b128 v[190:193], v149 offset:4096
	ds_read_b128 v[202:205], v149 offset:5120
	ds_read_b128 v[206:209], v149 offset:6144
	ds_read_b128 v[220:223], v149 offset:7168
	global_load_lds_dwordx4 v[144:145], off
	v_lshl_add_u64 v[144:145], s[34:35], 0, v[134:135]
	s_add_i32 m0, s79, 0xe000
	s_nop 0
	global_load_lds_dwordx4 v[144:145], off
	s_waitcnt vmcnt(8)
	s_waitcnt lgkmcnt(0)
	s_setprio 1
	s_barrier
	v_mfma_f32_16x16x32_bf16 v[126:129], v[136:139], v[174:177], v[126:129]
	v_mfma_f32_16x16x32_bf16 v[98:101], v[150:153], v[174:177], v[98:101]
	v_mfma_f32_16x16x32_bf16 v[122:125], v[136:139], v[182:185], v[122:125]
	v_mfma_f32_16x16x32_bf16 v[94:97], v[150:153], v[182:185], v[94:97]
	v_mfma_f32_16x16x32_bf16 v[118:121], v[136:139], v[190:193], v[118:121]
	v_mfma_f32_16x16x32_bf16 v[86:89], v[150:153], v[190:193], v[86:89]
	v_mfma_f32_16x16x32_bf16 v[114:117], v[136:139], v[206:209], v[114:117]
	v_mfma_f32_16x16x32_bf16 v[82:85], v[150:153], v[206:209], v[82:85]
	v_mfma_f32_16x16x32_bf16 v[126:129], v[140:143], v[178:181], v[126:129]
	v_mfma_f32_16x16x32_bf16 v[98:101], v[154:157], v[178:181], v[98:101]
	v_mfma_f32_16x16x32_bf16 v[122:125], v[140:143], v[186:189], v[122:125]
	v_mfma_f32_16x16x32_bf16 v[94:97], v[154:157], v[186:189], v[94:97]
	v_mfma_f32_16x16x32_bf16 v[118:121], v[140:143], v[202:205], v[118:121]
	v_mfma_f32_16x16x32_bf16 v[86:89], v[154:157], v[202:205], v[86:89]
	v_mfma_f32_16x16x32_bf16 v[114:117], v[140:143], v[220:223], v[114:117]
	v_mfma_f32_16x16x32_bf16 v[82:85], v[154:157], v[220:223], v[82:85]
	v_mfma_f32_16x16x32_bf16 v[70:73], v[158:161], v[174:177], v[70:73]
	v_mfma_f32_16x16x32_bf16 v[42:45], v[166:169], v[174:177], v[42:45]
	v_mfma_f32_16x16x32_bf16 v[62:65], v[158:161], v[182:185], v[62:65]
	v_mfma_f32_16x16x32_bf16 v[34:37], v[166:169], v[182:185], v[34:37]
	v_mfma_f32_16x16x32_bf16 v[54:57], v[158:161], v[190:193], v[54:57]
	v_mfma_f32_16x16x32_bf16 v[26:29], v[166:169], v[190:193], v[26:29]
	v_mfma_f32_16x16x32_bf16 v[50:53], v[158:161], v[206:209], v[50:53]
	v_mfma_f32_16x16x32_bf16 v[18:21], v[166:169], v[206:209], v[18:21]
	v_mfma_f32_16x16x32_bf16 v[70:73], v[162:165], v[178:181], v[70:73]
	v_mfma_f32_16x16x32_bf16 v[42:45], v[170:173], v[178:181], v[42:45]
	v_mfma_f32_16x16x32_bf16 v[62:65], v[162:165], v[186:189], v[62:65]
	v_mfma_f32_16x16x32_bf16 v[34:37], v[170:173], v[186:189], v[34:37]
	v_mfma_f32_16x16x32_bf16 v[54:57], v[162:165], v[202:205], v[54:57]
	v_mfma_f32_16x16x32_bf16 v[26:29], v[170:173], v[202:205], v[26:29]
	v_mfma_f32_16x16x32_bf16 v[50:53], v[162:165], v[220:223], v[50:53]
	v_mfma_f32_16x16x32_bf16 v[18:21], v[170:173], v[220:223], v[18:21]
	s_setprio 0
	s_barrier
	s_add_i32 s62, s62, s78
	v_lshl_add_u64 v[144:145], s[60:61], 0, v[0:1]
	s_mov_b32 m0, s62
	ds_read_b128 v[174:177], v149 offset:16384
	ds_read_b128 v[178:181], v149 offset:17408
	ds_read_b128 v[182:185], v149 offset:18432
	ds_read_b128 v[186:189], v149 offset:19456
	ds_read_b128 v[190:193], v149 offset:20480
	ds_read_b128 v[202:205], v149 offset:21504
	ds_read_b128 v[206:209], v149 offset:22528
	ds_read_b128 v[220:223], v149 offset:23552
	global_load_lds_dwordx4 v[144:145], off
	s_add_i32 m0, s62, 0x2000
	v_lshl_add_u64 v[194:195], s[60:61], 0, v[130:131]
	s_add_u32 s60, s60, s80
	s_addc_u32 s61, s61, 0
	s_add_i32 s59, s59, s78
	global_load_lds_dwordx4 v[194:195], off
	v_lshl_add_u64 v[198:199], s[60:61], 0, v[0:1]
	s_mov_b32 m0, s59
	v_lshl_add_u64 v[200:201], s[60:61], 0, v[130:131]
	global_load_lds_dwordx4 v[198:199], off
	s_add_i32 m0, s59, 0x2000
	v_lshl_add_u64 v[210:211], s[36:37], 0, v[0:1]
	global_load_lds_dwordx4 v[200:201], off
	s_mov_b32 m0, s79
	v_lshl_add_u64 v[212:213], s[36:37], 0, v[130:131]
	global_load_lds_dwordx4 v[210:211], off
	s_mov_b32 m0, s46
	s_nop 0
	global_load_lds_dwordx4 v[212:213], off
	s_waitcnt vmcnt(8)
	s_waitcnt lgkmcnt(0)
	s_setprio 1
	s_barrier
	v_mfma_f32_16x16x32_bf16 v[110:113], v[136:139], v[174:177], v[110:113]
	v_mfma_f32_16x16x32_bf16 v[78:81], v[150:153], v[174:177], v[78:81]
	v_mfma_f32_16x16x32_bf16 v[106:109], v[136:139], v[182:185], v[106:109]
	v_mfma_f32_16x16x32_bf16 v[74:77], v[150:153], v[182:185], v[74:77]
	v_mfma_f32_16x16x32_bf16 v[102:105], v[136:139], v[190:193], v[102:105]
	v_mfma_f32_16x16x32_bf16 v[66:69], v[150:153], v[190:193], v[66:69]
	v_mfma_f32_16x16x32_bf16 v[90:93], v[136:139], v[206:209], v[90:93]
	v_mfma_f32_16x16x32_bf16 v[58:61], v[150:153], v[206:209], v[58:61]
	v_mfma_f32_16x16x32_bf16 v[110:113], v[140:143], v[178:181], v[110:113]
	v_mfma_f32_16x16x32_bf16 v[78:81], v[154:157], v[178:181], v[78:81]
	v_mfma_f32_16x16x32_bf16 v[106:109], v[140:143], v[186:189], v[106:109]
	v_mfma_f32_16x16x32_bf16 v[74:77], v[154:157], v[186:189], v[74:77]
	v_mfma_f32_16x16x32_bf16 v[102:105], v[140:143], v[202:205], v[102:105]
	v_mfma_f32_16x16x32_bf16 v[66:69], v[154:157], v[202:205], v[66:69]
	v_mfma_f32_16x16x32_bf16 v[90:93], v[140:143], v[220:223], v[90:93]
	v_mfma_f32_16x16x32_bf16 v[58:61], v[154:157], v[220:223], v[58:61]
	v_mfma_f32_16x16x32_bf16 v[46:49], v[158:161], v[174:177], v[46:49]
	v_mfma_f32_16x16x32_bf16 v[14:17], v[166:169], v[174:177], v[14:17]
	v_mfma_f32_16x16x32_bf16 v[38:41], v[158:161], v[182:185], v[38:41]
	v_mfma_f32_16x16x32_bf16 v[10:13], v[166:169], v[182:185], v[10:13]
	v_mfma_f32_16x16x32_bf16 v[30:33], v[158:161], v[190:193], v[30:33]
	v_mfma_f32_16x16x32_bf16 v[6:9], v[166:169], v[190:193], v[6:9]
	v_mfma_f32_16x16x32_bf16 v[22:25], v[158:161], v[206:209], v[22:25]
	v_mfma_f32_16x16x32_bf16 v[2:5], v[166:169], v[206:209], v[2:5]
	v_mfma_f32_16x16x32_bf16 v[46:49], v[162:165], v[178:181], v[46:49]
	v_mfma_f32_16x16x32_bf16 v[14:17], v[170:173], v[178:181], v[14:17]
	v_mfma_f32_16x16x32_bf16 v[38:41], v[162:165], v[186:189], v[38:41]
	v_mfma_f32_16x16x32_bf16 v[10:13], v[170:173], v[186:189], v[10:13]
	v_mfma_f32_16x16x32_bf16 v[30:33], v[162:165], v[202:205], v[30:33]
	v_mfma_f32_16x16x32_bf16 v[6:9], v[170:173], v[202:205], v[6:9]
	v_mfma_f32_16x16x32_bf16 v[22:25], v[162:165], v[220:223], v[22:25]
	v_mfma_f32_16x16x32_bf16 v[2:5], v[170:173], v[220:223], v[2:5]
	s_setprio 0
	s_barrier
	s_add_i32 s59, 0, 0x18000
	s_add_i32 s60, 0, 0x1c000
	v_add_u32_e32 v154, s59, v147
	v_add_u32_e32 v170, s60, v147
	ds_read_b128 v[136:139], v154
	ds_read_b128 v[140:143], v154 offset:1024
	ds_read_b128 v[150:153], v154 offset:2048
	ds_read_b128 v[154:157], v154 offset:3072
	ds_read_b128 v[158:161], v170
	ds_read_b128 v[162:165], v170 offset:1024
	ds_read_b128 v[166:169], v170 offset:2048
	ds_read_b128 v[170:173], v170 offset:3072
	s_add_u32 s36, s36, s80
	s_addc_u32 s37, s37, 0
	s_mov_b32 m0, s47
	v_lshl_add_u64 v[214:215], s[36:37], 0, v[0:1]
	ds_read_b128 v[174:177], v149 offset:32768
	ds_read_b128 v[178:181], v149 offset:33792
	ds_read_b128 v[182:185], v149 offset:34816
	ds_read_b128 v[186:189], v149 offset:35840
	ds_read_b128 v[190:193], v149 offset:36864
	ds_read_b128 v[202:205], v149 offset:37888
	ds_read_b128 v[206:209], v149 offset:38912
	ds_read_b128 v[220:223], v149 offset:39936
	global_load_lds_dwordx4 v[214:215], off
	v_lshl_add_u64 v[214:215], s[36:37], 0, v[130:131]
	s_mov_b32 m0, s82
	s_nop 0
	global_load_lds_dwordx4 v[214:215], off
	s_waitcnt vmcnt(8)
	s_waitcnt lgkmcnt(0)
	s_setprio 1
	s_barrier
	v_mfma_f32_16x16x32_bf16 v[126:129], v[136:139], v[174:177], v[126:129]
	v_mfma_f32_16x16x32_bf16 v[98:101], v[150:153], v[174:177], v[98:101]
	v_mfma_f32_16x16x32_bf16 v[122:125], v[136:139], v[182:185], v[122:125]
	v_mfma_f32_16x16x32_bf16 v[94:97], v[150:153], v[182:185], v[94:97]
	v_mfma_f32_16x16x32_bf16 v[118:121], v[136:139], v[190:193], v[118:121]
	v_mfma_f32_16x16x32_bf16 v[86:89], v[150:153], v[190:193], v[86:89]
	v_mfma_f32_16x16x32_bf16 v[114:117], v[136:139], v[206:209], v[114:117]
	v_mfma_f32_16x16x32_bf16 v[82:85], v[150:153], v[206:209], v[82:85]
	v_mfma_f32_16x16x32_bf16 v[126:129], v[140:143], v[178:181], v[126:129]
	v_mfma_f32_16x16x32_bf16 v[98:101], v[154:157], v[178:181], v[98:101]
	v_mfma_f32_16x16x32_bf16 v[122:125], v[140:143], v[186:189], v[122:125]
	v_mfma_f32_16x16x32_bf16 v[94:97], v[154:157], v[186:189], v[94:97]
	v_mfma_f32_16x16x32_bf16 v[118:121], v[140:143], v[202:205], v[118:121]
	v_mfma_f32_16x16x32_bf16 v[86:89], v[154:157], v[202:205], v[86:89]
	v_mfma_f32_16x16x32_bf16 v[114:117], v[140:143], v[220:223], v[114:117]
	v_mfma_f32_16x16x32_bf16 v[82:85], v[154:157], v[220:223], v[82:85]
	v_mfma_f32_16x16x32_bf16 v[70:73], v[158:161], v[174:177], v[70:73]
	v_mfma_f32_16x16x32_bf16 v[42:45], v[166:169], v[174:177], v[42:45]
	v_mfma_f32_16x16x32_bf16 v[62:65], v[158:161], v[182:185], v[62:65]
	v_mfma_f32_16x16x32_bf16 v[34:37], v[166:169], v[182:185], v[34:37]
	v_mfma_f32_16x16x32_bf16 v[54:57], v[158:161], v[190:193], v[54:57]
	v_mfma_f32_16x16x32_bf16 v[26:29], v[166:169], v[190:193], v[26:29]
	v_mfma_f32_16x16x32_bf16 v[50:53], v[158:161], v[206:209], v[50:53]
	v_mfma_f32_16x16x32_bf16 v[18:21], v[166:169], v[206:209], v[18:21]
	v_mfma_f32_16x16x32_bf16 v[70:73], v[162:165], v[178:181], v[70:73]
	v_mfma_f32_16x16x32_bf16 v[42:45], v[170:173], v[178:181], v[42:45]
	v_mfma_f32_16x16x32_bf16 v[62:65], v[162:165], v[186:189], v[62:65]
	v_mfma_f32_16x16x32_bf16 v[34:37], v[170:173], v[186:189], v[34:37]
	v_mfma_f32_16x16x32_bf16 v[54:57], v[162:165], v[202:205], v[54:57]
	v_mfma_f32_16x16x32_bf16 v[26:29], v[170:173], v[202:205], v[26:29]
	v_mfma_f32_16x16x32_bf16 v[50:53], v[162:165], v[220:223], v[50:53]
	v_mfma_f32_16x16x32_bf16 v[18:21], v[170:173], v[220:223], v[18:21]
	s_setprio 0
	s_barrier
	s_add_i32 s36, s59, s78
	v_lshl_add_u64 v[144:145], v[144:145], 0, s[84:85]
	s_mov_b32 m0, s36
	ds_read_b128 v[174:177], v149 offset:49152
	ds_read_b128 v[178:181], v149 offset:50176
	ds_read_b128 v[182:185], v149 offset:51200
	ds_read_b128 v[186:189], v149 offset:52224
	ds_read_b128 v[190:193], v149 offset:53248
	ds_read_b128 v[202:205], v149 offset:54272
	ds_read_b128 v[206:209], v149 offset:55296
	ds_read_b128 v[220:223], v149 offset:56320
	global_load_lds_dwordx4 v[144:145], off
	v_lshl_add_u64 v[144:145], v[194:195], 0, s[84:85]
	s_add_i32 m0, s36, 0x2000
	s_add_i32 s36, s60, s78
	global_load_lds_dwordx4 v[144:145], off
	v_lshl_add_u64 v[144:145], v[198:199], 0, s[84:85]
	s_mov_b32 m0, s36
	s_nop 0
	global_load_lds_dwordx4 v[144:145], off
	v_lshl_add_u64 v[144:145], v[200:201], 0, s[84:85]
	s_add_i32 m0, s36, 0x2000
	s_nop 0
	global_load_lds_dwordx4 v[144:145], off
	v_lshl_add_u64 v[144:145], v[210:211], 0, s[84:85]
	s_mov_b32 m0, s48
	s_nop 0
	global_load_lds_dwordx4 v[144:145], off
	v_lshl_add_u64 v[144:145], v[212:213], 0, s[84:85]
	s_mov_b32 m0, s49
	s_nop 0
	global_load_lds_dwordx4 v[144:145], off
	s_waitcnt vmcnt(8)
	s_waitcnt lgkmcnt(0)
	s_setprio 1
	s_barrier
	v_mfma_f32_16x16x32_bf16 v[110:113], v[136:139], v[174:177], v[110:113]
	v_mfma_f32_16x16x32_bf16 v[78:81], v[150:153], v[174:177], v[78:81]
	v_mfma_f32_16x16x32_bf16 v[106:109], v[136:139], v[182:185], v[106:109]
	v_mfma_f32_16x16x32_bf16 v[74:77], v[150:153], v[182:185], v[74:77]
	v_mfma_f32_16x16x32_bf16 v[102:105], v[136:139], v[190:193], v[102:105]
	v_mfma_f32_16x16x32_bf16 v[66:69], v[150:153], v[190:193], v[66:69]
	v_mfma_f32_16x16x32_bf16 v[90:93], v[136:139], v[206:209], v[90:93]
	v_mfma_f32_16x16x32_bf16 v[58:61], v[150:153], v[206:209], v[58:61]
	v_mfma_f32_16x16x32_bf16 v[110:113], v[140:143], v[178:181], v[110:113]
	v_mfma_f32_16x16x32_bf16 v[78:81], v[154:157], v[178:181], v[78:81]
	v_mfma_f32_16x16x32_bf16 v[106:109], v[140:143], v[186:189], v[106:109]
	v_mfma_f32_16x16x32_bf16 v[74:77], v[154:157], v[186:189], v[74:77]
	v_mfma_f32_16x16x32_bf16 v[102:105], v[140:143], v[202:205], v[102:105]
	v_mfma_f32_16x16x32_bf16 v[66:69], v[154:157], v[202:205], v[66:69]
	v_mfma_f32_16x16x32_bf16 v[90:93], v[140:143], v[220:223], v[90:93]
	v_mfma_f32_16x16x32_bf16 v[58:61], v[154:157], v[220:223], v[58:61]
	v_mfma_f32_16x16x32_bf16 v[46:49], v[158:161], v[174:177], v[46:49]
	v_mfma_f32_16x16x32_bf16 v[14:17], v[166:169], v[174:177], v[14:17]
	v_mfma_f32_16x16x32_bf16 v[38:41], v[158:161], v[182:185], v[38:41]
	v_mfma_f32_16x16x32_bf16 v[10:13], v[166:169], v[182:185], v[10:13]
	v_mfma_f32_16x16x32_bf16 v[30:33], v[158:161], v[190:193], v[30:33]
	v_mfma_f32_16x16x32_bf16 v[6:9], v[166:169], v[190:193], v[6:9]
	v_mfma_f32_16x16x32_bf16 v[22:25], v[158:161], v[206:209], v[22:25]
	v_mfma_f32_16x16x32_bf16 v[2:5], v[166:169], v[206:209], v[2:5]
	v_mfma_f32_16x16x32_bf16 v[46:49], v[162:165], v[178:181], v[46:49]
	v_mfma_f32_16x16x32_bf16 v[14:17], v[170:173], v[178:181], v[14:17]
	v_mfma_f32_16x16x32_bf16 v[38:41], v[162:165], v[186:189], v[38:41]
	v_mfma_f32_16x16x32_bf16 v[10:13], v[170:173], v[186:189], v[10:13]
	v_mfma_f32_16x16x32_bf16 v[30:33], v[162:165], v[202:205], v[30:33]
	v_mfma_f32_16x16x32_bf16 v[6:9], v[170:173], v[202:205], v[6:9]
	v_mfma_f32_16x16x32_bf16 v[22:25], v[162:165], v[220:223], v[22:25]
	v_mfma_f32_16x16x32_bf16 v[2:5], v[170:173], v[220:223], v[2:5]
	s_setprio 0
	s_barrier
	s_add_u32 s34, s34, 0x100
	s_addc_u32 s35, s35, 0
	s_add_u32 s56, s56, 0x100
	s_addc_u32 s57, s57, 0
	s_cmp_ge_u32 s58, s87
	s_mov_b32 s36, s58
	s_cbranch_scc0 .LBB0_438
	s_and_b64 vcc, exec, s[10:11]
	s_cbranch_vccz .LBB0_441
	s_barrier

.LBB0_483:
	s_add_i32 s61, s38, 2
	s_add_u32 s62, s20, s36
	s_addc_u32 s39, s21, s37
	s_add_u32 s64, s4, s36
	s_addc_u32 s63, s5, s37
	s_add_i32 s65, 0, 0x10000
	s_cmp_eq_u32 s56, s38
	s_cselect_b32 s39, s11, s39
	s_cselect_b32 s38, s10, s62
	v_add_u32_e32 v147, s65, v145
	s_cselect_b32 s63, s35, s63
	s_cselect_b32 s62, s34, s64
	s_add_i32 s64, 0, 0x14000
	ds_read_b128 v[148:151], v147
	ds_read_b128 v[152:155], v147 offset:1024
	ds_read_b128 v[156:159], v147 offset:2048
	ds_read_b128 v[160:163], v147 offset:3072
	v_add_u32_e32 v147, s64, v145
	ds_read_b128 v[164:167], v147
	ds_read_b128 v[168:171], v147 offset:1024
	ds_read_b128 v[172:175], v147 offset:2048
	ds_read_b128 v[176:179], v147 offset:3072
	v_lshl_add_u64 v[194:195], s[20:21], 0, v[142:143]
	s_add_i32 m0, s48, 0xc000
	ds_read_b128 v[180:183], v146
	ds_read_b128 v[184:187], v146 offset:1024
	ds_read_b128 v[190:193], v146 offset:2048
	ds_read_b128 v[202:205], v146 offset:3072
	ds_read_b128 v[206:209], v146 offset:4096
	ds_read_b128 v[220:223], v146 offset:5120
	ds_read_b128 v[224:227], v146 offset:6144
	ds_read_b128 v[228:231], v146 offset:7168
	global_load_lds_dwordx4 v[194:195], off
	v_lshl_add_u64 v[194:195], s[20:21], 0, v[140:141]
	s_add_i32 m0, s48, 0xe000
	s_nop 0
	global_load_lds_dwordx4 v[194:195], off
	s_waitcnt vmcnt(8)
	s_waitcnt lgkmcnt(0)
	s_setprio 1
	s_barrier
	v_mfma_f32_16x16x32_bf16 v[126:129], v[148:151], v[180:183], v[126:129]
	v_mfma_f32_16x16x32_bf16 v[122:125], v[156:159], v[180:183], v[122:125]
	v_mfma_f32_16x16x32_bf16 v[118:121], v[148:151], v[190:193], v[118:121]
	v_mfma_f32_16x16x32_bf16 v[114:117], v[156:159], v[190:193], v[114:117]
	v_mfma_f32_16x16x32_bf16 v[110:113], v[148:151], v[206:209], v[110:113]
	v_mfma_f32_16x16x32_bf16 v[106:109], v[156:159], v[206:209], v[106:109]
	v_mfma_f32_16x16x32_bf16 v[102:105], v[148:151], v[224:227], v[102:105]
	v_mfma_f32_16x16x32_bf16 v[98:101], v[156:159], v[224:227], v[98:101]
	v_mfma_f32_16x16x32_bf16 v[126:129], v[152:155], v[184:187], v[126:129]
	v_mfma_f32_16x16x32_bf16 v[122:125], v[160:163], v[184:187], v[122:125]
	v_mfma_f32_16x16x32_bf16 v[118:121], v[152:155], v[202:205], v[118:121]
	v_mfma_f32_16x16x32_bf16 v[114:117], v[160:163], v[202:205], v[114:117]
	v_mfma_f32_16x16x32_bf16 v[110:113], v[152:155], v[220:223], v[110:113]
	v_mfma_f32_16x16x32_bf16 v[106:109], v[160:163], v[220:223], v[106:109]
	v_mfma_f32_16x16x32_bf16 v[102:105], v[152:155], v[228:231], v[102:105]
	v_mfma_f32_16x16x32_bf16 v[98:101], v[160:163], v[228:231], v[98:101]
	v_mfma_f32_16x16x32_bf16 v[62:65], v[164:167], v[180:183], v[62:65]
	v_mfma_f32_16x16x32_bf16 v[58:61], v[172:175], v[180:183], v[58:61]
	v_mfma_f32_16x16x32_bf16 v[54:57], v[164:167], v[190:193], v[54:57]
	v_mfma_f32_16x16x32_bf16 v[50:53], v[172:175], v[190:193], v[50:53]
	v_mfma_f32_16x16x32_bf16 v[46:49], v[164:167], v[206:209], v[46:49]
	v_mfma_f32_16x16x32_bf16 v[42:45], v[172:175], v[206:209], v[42:45]
	v_mfma_f32_16x16x32_bf16 v[38:41], v[164:167], v[224:227], v[38:41]
	v_mfma_f32_16x16x32_bf16 v[34:37], v[172:175], v[224:227], v[34:37]
	v_mfma_f32_16x16x32_bf16 v[62:65], v[168:171], v[184:187], v[62:65]
	v_mfma_f32_16x16x32_bf16 v[58:61], v[176:179], v[184:187], v[58:61]
	v_mfma_f32_16x16x32_bf16 v[54:57], v[168:171], v[202:205], v[54:57]
	v_mfma_f32_16x16x32_bf16 v[50:53], v[176:179], v[202:205], v[50:53]
	v_mfma_f32_16x16x32_bf16 v[46:49], v[168:171], v[220:223], v[46:49]
	v_mfma_f32_16x16x32_bf16 v[42:45], v[176:179], v[220:223], v[42:45]
	v_mfma_f32_16x16x32_bf16 v[38:41], v[168:171], v[228:231], v[38:41]
	v_mfma_f32_16x16x32_bf16 v[34:37], v[176:179], v[228:231], v[34:37]
	s_setprio 0
	s_barrier
	s_add_i32 s65, s65, s47
	v_lshl_add_u64 v[194:195], s[62:63], 0, v[0:1]
	s_mov_b32 m0, s65
	ds_read_b128 v[180:183], v146 offset:16384
	ds_read_b128 v[184:187], v146 offset:17408
	ds_read_b128 v[190:193], v146 offset:18432
	ds_read_b128 v[202:205], v146 offset:19456
	ds_read_b128 v[206:209], v146 offset:20480
	ds_read_b128 v[220:223], v146 offset:21504
	ds_read_b128 v[224:227], v146 offset:22528
	ds_read_b128 v[228:231], v146 offset:23552
	global_load_lds_dwordx4 v[194:195], off
	s_add_i32 m0, s65, 0x2000
	v_lshl_add_u64 v[198:199], s[62:63], 0, v[134:135]
	s_add_u32 s62, s62, s80
	s_addc_u32 s63, s63, 0
	s_add_i32 s64, s64, s47
	global_load_lds_dwordx4 v[198:199], off
	v_lshl_add_u64 v[200:201], s[62:63], 0, v[0:1]
	s_mov_b32 m0, s64
	v_lshl_add_u64 v[210:211], s[62:63], 0, v[134:135]
	global_load_lds_dwordx4 v[200:201], off
	s_add_i32 m0, s64, 0x2000
	v_lshl_add_u64 v[212:213], s[38:39], 0, v[130:131]
	global_load_lds_dwordx4 v[210:211], off
	s_mov_b32 m0, s48
	v_lshl_add_u64 v[214:215], s[38:39], 0, v[132:133]
	global_load_lds_dwordx4 v[212:213], off
	s_mov_b32 m0, s50
	s_nop 0
	global_load_lds_dwordx4 v[214:215], off
	s_waitcnt vmcnt(8)
	s_waitcnt lgkmcnt(0)
	s_setprio 1
	s_barrier
	v_mfma_f32_16x16x32_bf16 v[94:97], v[148:151], v[180:183], v[94:97]
	v_mfma_f32_16x16x32_bf16 v[90:93], v[156:159], v[180:183], v[90:93]
	v_mfma_f32_16x16x32_bf16 v[86:89], v[148:151], v[190:193], v[86:89]
	v_mfma_f32_16x16x32_bf16 v[82:85], v[156:159], v[190:193], v[82:85]
	v_mfma_f32_16x16x32_bf16 v[78:81], v[148:151], v[206:209], v[78:81]
	v_mfma_f32_16x16x32_bf16 v[74:77], v[156:159], v[206:209], v[74:77]
	v_mfma_f32_16x16x32_bf16 v[70:73], v[148:151], v[224:227], v[70:73]
	v_mfma_f32_16x16x32_bf16 v[66:69], v[156:159], v[224:227], v[66:69]
	v_mfma_f32_16x16x32_bf16 v[94:97], v[152:155], v[184:187], v[94:97]
	v_mfma_f32_16x16x32_bf16 v[90:93], v[160:163], v[184:187], v[90:93]
	v_mfma_f32_16x16x32_bf16 v[86:89], v[152:155], v[202:205], v[86:89]
	v_mfma_f32_16x16x32_bf16 v[82:85], v[160:163], v[202:205], v[82:85]
	v_mfma_f32_16x16x32_bf16 v[78:81], v[152:155], v[220:223], v[78:81]
	v_mfma_f32_16x16x32_bf16 v[74:77], v[160:163], v[220:223], v[74:77]
	v_mfma_f32_16x16x32_bf16 v[70:73], v[152:155], v[228:231], v[70:73]
	v_mfma_f32_16x16x32_bf16 v[66:69], v[160:163], v[228:231], v[66:69]
	v_mfma_f32_16x16x32_bf16 v[30:33], v[164:167], v[180:183], v[30:33]
	v_mfma_f32_16x16x32_bf16 v[26:29], v[172:175], v[180:183], v[26:29]
	v_mfma_f32_16x16x32_bf16 v[22:25], v[164:167], v[190:193], v[22:25]
	v_mfma_f32_16x16x32_bf16 v[18:21], v[172:175], v[190:193], v[18:21]
	v_mfma_f32_16x16x32_bf16 v[14:17], v[164:167], v[206:209], v[14:17]
	v_mfma_f32_16x16x32_bf16 v[10:13], v[172:175], v[206:209], v[10:13]
	v_mfma_f32_16x16x32_bf16 v[6:9], v[164:167], v[224:227], v[6:9]
	v_mfma_f32_16x16x32_bf16 v[2:5], v[172:175], v[224:227], v[2:5]
	v_mfma_f32_16x16x32_bf16 v[30:33], v[168:171], v[184:187], v[30:33]
	v_mfma_f32_16x16x32_bf16 v[26:29], v[176:179], v[184:187], v[26:29]
	v_mfma_f32_16x16x32_bf16 v[22:25], v[168:171], v[202:205], v[22:25]
	v_mfma_f32_16x16x32_bf16 v[18:21], v[176:179], v[202:205], v[18:21]
	v_mfma_f32_16x16x32_bf16 v[14:17], v[168:171], v[220:223], v[14:17]
	v_mfma_f32_16x16x32_bf16 v[10:13], v[176:179], v[220:223], v[10:13]
	v_mfma_f32_16x16x32_bf16 v[6:9], v[168:171], v[228:231], v[6:9]
	v_mfma_f32_16x16x32_bf16 v[2:5], v[176:179], v[228:231], v[2:5]
	s_setprio 0
	s_barrier
	s_add_i32 s62, 0, 0x18000
	v_add_u32_e32 v147, s62, v145
	s_add_i32 s63, 0, 0x1c000
	ds_read_b128 v[148:151], v147
	ds_read_b128 v[152:155], v147 offset:1024
	ds_read_b128 v[156:159], v147 offset:2048
	ds_read_b128 v[160:163], v147 offset:3072
	v_add_u32_e32 v147, s63, v145
	ds_read_b128 v[164:167], v147
	ds_read_b128 v[168:171], v147 offset:1024
	ds_read_b128 v[172:175], v147 offset:2048
	ds_read_b128 v[176:179], v147 offset:3072
	s_add_u32 s38, s38, s80
	s_addc_u32 s39, s39, 0
	s_mov_b32 m0, s51
	v_lshl_add_u64 v[216:217], s[38:39], 0, v[130:131]
	ds_read_b128 v[180:183], v146 offset:32768
	ds_read_b128 v[184:187], v146 offset:33792
	ds_read_b128 v[190:193], v146 offset:34816
	ds_read_b128 v[202:205], v146 offset:35840
	ds_read_b128 v[206:209], v146 offset:36864
	ds_read_b128 v[220:223], v146 offset:37888
	ds_read_b128 v[224:227], v146 offset:38912
	ds_read_b128 v[228:231], v146 offset:39936
	global_load_lds_dwordx4 v[216:217], off
	v_lshl_add_u64 v[216:217], s[38:39], 0, v[132:133]
	s_mov_b32 m0, s52
	s_nop 0
	global_load_lds_dwordx4 v[216:217], off
	s_waitcnt vmcnt(8)
	s_waitcnt lgkmcnt(0)
	s_setprio 1
	s_barrier
	v_mfma_f32_16x16x32_bf16 v[126:129], v[148:151], v[180:183], v[126:129]
	v_mfma_f32_16x16x32_bf16 v[122:125], v[156:159], v[180:183], v[122:125]
	v_mfma_f32_16x16x32_bf16 v[118:121], v[148:151], v[190:193], v[118:121]
	v_mfma_f32_16x16x32_bf16 v[114:117], v[156:159], v[190:193], v[114:117]
	v_mfma_f32_16x16x32_bf16 v[110:113], v[148:151], v[206:209], v[110:113]
	v_mfma_f32_16x16x32_bf16 v[106:109], v[156:159], v[206:209], v[106:109]
	v_mfma_f32_16x16x32_bf16 v[102:105], v[148:151], v[224:227], v[102:105]
	v_mfma_f32_16x16x32_bf16 v[98:101], v[156:159], v[224:227], v[98:101]
	v_mfma_f32_16x16x32_bf16 v[126:129], v[152:155], v[184:187], v[126:129]
	v_mfma_f32_16x16x32_bf16 v[122:125], v[160:163], v[184:187], v[122:125]
	v_mfma_f32_16x16x32_bf16 v[118:121], v[152:155], v[202:205], v[118:121]
	v_mfma_f32_16x16x32_bf16 v[114:117], v[160:163], v[202:205], v[114:117]
	v_mfma_f32_16x16x32_bf16 v[110:113], v[152:155], v[220:223], v[110:113]
	v_mfma_f32_16x16x32_bf16 v[106:109], v[160:163], v[220:223], v[106:109]
	v_mfma_f32_16x16x32_bf16 v[102:105], v[152:155], v[228:231], v[102:105]
	v_mfma_f32_16x16x32_bf16 v[98:101], v[160:163], v[228:231], v[98:101]
	v_mfma_f32_16x16x32_bf16 v[62:65], v[164:167], v[180:183], v[62:65]
	v_mfma_f32_16x16x32_bf16 v[58:61], v[172:175], v[180:183], v[58:61]
	v_mfma_f32_16x16x32_bf16 v[54:57], v[164:167], v[190:193], v[54:57]
	v_mfma_f32_16x16x32_bf16 v[50:53], v[172:175], v[190:193], v[50:53]
	v_mfma_f32_16x16x32_bf16 v[46:49], v[164:167], v[206:209], v[46:49]
	v_mfma_f32_16x16x32_bf16 v[42:45], v[172:175], v[206:209], v[42:45]
	v_mfma_f32_16x16x32_bf16 v[38:41], v[164:167], v[224:227], v[38:41]
	v_mfma_f32_16x16x32_bf16 v[34:37], v[172:175], v[224:227], v[34:37]
	v_mfma_f32_16x16x32_bf16 v[62:65], v[168:171], v[184:187], v[62:65]
	v_mfma_f32_16x16x32_bf16 v[58:61], v[176:179], v[184:187], v[58:61]
	v_mfma_f32_16x16x32_bf16 v[54:57], v[168:171], v[202:205], v[54:57]
	v_mfma_f32_16x16x32_bf16 v[50:53], v[176:179], v[202:205], v[50:53]
	v_mfma_f32_16x16x32_bf16 v[46:49], v[168:171], v[220:223], v[46:49]
	v_mfma_f32_16x16x32_bf16 v[42:45], v[176:179], v[220:223], v[42:45]
	v_mfma_f32_16x16x32_bf16 v[38:41], v[168:171], v[228:231], v[38:41]
	v_mfma_f32_16x16x32_bf16 v[34:37], v[176:179], v[228:231], v[34:37]
	s_setprio 0
	s_barrier
	s_add_i32 s38, s62, s47
	v_lshl_add_u64 v[194:195], v[194:195], 0, s[84:85]
	s_mov_b32 m0, s38
	ds_read_b128 v[180:183], v146 offset:49152
	ds_read_b128 v[184:187], v146 offset:50176
	ds_read_b128 v[190:193], v146 offset:51200
	ds_read_b128 v[202:205], v146 offset:52224
	ds_read_b128 v[206:209], v146 offset:53248
	ds_read_b128 v[220:223], v146 offset:54272
	ds_read_b128 v[224:227], v146 offset:55296
	ds_read_b128 v[228:231], v146 offset:56320
	global_load_lds_dwordx4 v[194:195], off
	v_lshl_add_u64 v[194:195], v[198:199], 0, s[84:85]
	s_add_i32 m0, s38, 0x2000
	s_add_i32 s38, s63, s47
	global_load_lds_dwordx4 v[194:195], off
	v_lshl_add_u64 v[194:195], v[200:201], 0, s[84:85]
	s_mov_b32 m0, s38
	s_nop 0
	global_load_lds_dwordx4 v[194:195], off
	v_lshl_add_u64 v[194:195], v[210:211], 0, s[84:85]
	s_add_i32 m0, s38, 0x2000
	s_nop 0
	global_load_lds_dwordx4 v[194:195], off
	v_lshl_add_u64 v[194:195], v[212:213], 0, s[84:85]
	s_mov_b32 m0, s54
	s_nop 0
	global_load_lds_dwordx4 v[194:195], off
	v_lshl_add_u64 v[194:195], v[214:215], 0, s[84:85]
	s_mov_b32 m0, s55
	s_nop 0
	global_load_lds_dwordx4 v[194:195], off
	s_waitcnt vmcnt(8)
	s_waitcnt lgkmcnt(0)
	s_setprio 1
	s_barrier
	v_mfma_f32_16x16x32_bf16 v[94:97], v[148:151], v[180:183], v[94:97]
	v_mfma_f32_16x16x32_bf16 v[90:93], v[156:159], v[180:183], v[90:93]
	v_mfma_f32_16x16x32_bf16 v[86:89], v[148:151], v[190:193], v[86:89]
	v_mfma_f32_16x16x32_bf16 v[82:85], v[156:159], v[190:193], v[82:85]
	v_mfma_f32_16x16x32_bf16 v[78:81], v[148:151], v[206:209], v[78:81]
	v_mfma_f32_16x16x32_bf16 v[74:77], v[156:159], v[206:209], v[74:77]
	v_mfma_f32_16x16x32_bf16 v[70:73], v[148:151], v[224:227], v[70:73]
	v_mfma_f32_16x16x32_bf16 v[66:69], v[156:159], v[224:227], v[66:69]
	v_mfma_f32_16x16x32_bf16 v[94:97], v[152:155], v[184:187], v[94:97]
	v_mfma_f32_16x16x32_bf16 v[90:93], v[160:163], v[184:187], v[90:93]
	v_mfma_f32_16x16x32_bf16 v[86:89], v[152:155], v[202:205], v[86:89]
	v_mfma_f32_16x16x32_bf16 v[82:85], v[160:163], v[202:205], v[82:85]
	v_mfma_f32_16x16x32_bf16 v[78:81], v[152:155], v[220:223], v[78:81]
	v_mfma_f32_16x16x32_bf16 v[74:77], v[160:163], v[220:223], v[74:77]
	v_mfma_f32_16x16x32_bf16 v[70:73], v[152:155], v[228:231], v[70:73]
	v_mfma_f32_16x16x32_bf16 v[66:69], v[160:163], v[228:231], v[66:69]
	v_mfma_f32_16x16x32_bf16 v[30:33], v[164:167], v[180:183], v[30:33]
	v_mfma_f32_16x16x32_bf16 v[26:29], v[172:175], v[180:183], v[26:29]
	v_mfma_f32_16x16x32_bf16 v[22:25], v[164:167], v[190:193], v[22:25]
	v_mfma_f32_16x16x32_bf16 v[18:21], v[172:175], v[190:193], v[18:21]
	v_mfma_f32_16x16x32_bf16 v[14:17], v[164:167], v[206:209], v[14:17]
	v_mfma_f32_16x16x32_bf16 v[10:13], v[172:175], v[206:209], v[10:13]
	v_mfma_f32_16x16x32_bf16 v[6:9], v[164:167], v[224:227], v[6:9]
	v_mfma_f32_16x16x32_bf16 v[2:5], v[172:175], v[224:227], v[2:5]
	v_mfma_f32_16x16x32_bf16 v[30:33], v[168:171], v[184:187], v[30:33]
	v_mfma_f32_16x16x32_bf16 v[26:29], v[176:179], v[184:187], v[26:29]
	v_mfma_f32_16x16x32_bf16 v[22:25], v[168:171], v[202:205], v[22:25]
	v_mfma_f32_16x16x32_bf16 v[18:21], v[176:179], v[202:205], v[18:21]
	v_mfma_f32_16x16x32_bf16 v[14:17], v[168:171], v[220:223], v[14:17]
	v_mfma_f32_16x16x32_bf16 v[10:13], v[176:179], v[220:223], v[10:13]
	v_mfma_f32_16x16x32_bf16 v[6:9], v[168:171], v[228:231], v[6:9]
	v_mfma_f32_16x16x32_bf16 v[2:5], v[176:179], v[228:231], v[2:5]
	s_setprio 0
	s_barrier
	s_add_u32 s36, s36, 0x100
	s_addc_u32 s37, s37, 0
	v_lshl_add_u64 v[142:143], v[142:143], 0, s[88:89]
	v_lshl_add_u64 v[140:141], v[140:141], 0, s[88:89]
	s_cmp_ge_u32 s61, s53
	s_mov_b32 s38, s61
	s_cbranch_scc0 .LBB0_483
	s_and_b64 vcc, exec, s[8:9]
	s_cbranch_vccnz .LBB0_471
	v_mov_b32_e32 v2, 0
	s_mov_b32 s2, s58
	s_mov_b32 s78, s59
	s_mov_b64 s[4:5], s[34:35]
	s_mov_b64 s[20:21], s[10:11]
	s_mov_b32 s57, s60
	v_mov_b32_e32 v3, v2
	v_mov_b32_e32 v4, v2
	v_mov_b32_e32 v5, v2
	v_mov_b32_e32 v6, v2
	v_mov_b32_e32 v7, v2
	v_mov_b32_e32 v8, v2
	v_mov_b32_e32 v9, v2
	v_mov_b32_e32 v10, v2
	v_mov_b32_e32 v11, v2
	v_mov_b32_e32 v12, v2
	v_mov_b32_e32 v13, v2
	v_mov_b32_e32 v14, v2
	v_mov_b32_e32 v15, v2
	v_mov_b32_e32 v16, v2
	v_mov_b32_e32 v17, v2
	v_mov_b32_e32 v18, v2
	v_mov_b32_e32 v19, v2
	v_mov_b32_e32 v20, v2
	v_mov_b32_e32 v21, v2
	v_mov_b32_e32 v22, v2
	v_mov_b32_e32 v23, v2
	v_mov_b32_e32 v24, v2
	v_mov_b32_e32 v25, v2
	v_mov_b32_e32 v26, v2
	v_mov_b32_e32 v27, v2
	v_mov_b32_e32 v28, v2
	v_mov_b32_e32 v29, v2
	v_mov_b32_e32 v30, v2
	v_mov_b32_e32 v31, v2
	v_mov_b32_e32 v32, v2
	v_mov_b32_e32 v33, v2
	v_mov_b32_e32 v66, v2
	v_mov_b32_e32 v67, v2
	v_mov_b32_e32 v68, v2
	v_mov_b32_e32 v69, v2
	v_mov_b32_e32 v70, v2
	v_mov_b32_e32 v71, v2
	v_mov_b32_e32 v72, v2
	v_mov_b32_e32 v73, v2
	v_mov_b32_e32 v74, v2
	v_mov_b32_e32 v75, v2
	v_mov_b32_e32 v76, v2
	v_mov_b32_e32 v77, v2
	v_mov_b32_e32 v78, v2
	v_mov_b32_e32 v79, v2
	v_mov_b32_e32 v80, v2
	v_mov_b32_e32 v81, v2
	v_mov_b32_e32 v82, v2
	v_mov_b32_e32 v83, v2
	v_mov_b32_e32 v84, v2
	v_mov_b32_e32 v85, v2
	v_mov_b32_e32 v86, v2
	v_mov_b32_e32 v87, v2
	v_mov_b32_e32 v88, v2
	v_mov_b32_e32 v89, v2
	v_mov_b32_e32 v90, v2
	v_mov_b32_e32 v91, v2
	v_mov_b32_e32 v92, v2
	v_mov_b32_e32 v93, v2
	v_mov_b32_e32 v94, v2
	v_mov_b32_e32 v95, v2
	v_mov_b32_e32 v96, v2
	v_mov_b32_e32 v97, v2
	v_mov_b32_e32 v34, v2
	v_mov_b32_e32 v35, v2
	v_mov_b32_e32 v36, v2
	v_mov_b32_e32 v37, v2
	v_mov_b32_e32 v38, v2
	v_mov_b32_e32 v39, v2
	v_mov_b32_e32 v40, v2
	v_mov_b32_e32 v41, v2
	v_mov_b32_e32 v42, v2
	v_mov_b32_e32 v43, v2
	v_mov_b32_e32 v44, v2
	v_mov_b32_e32 v45, v2
	v_mov_b32_e32 v46, v2
	v_mov_b32_e32 v47, v2
	v_mov_b32_e32 v48, v2
	v_mov_b32_e32 v49, v2
	v_mov_b32_e32 v50, v2
	v_mov_b32_e32 v51, v2
	v_mov_b32_e32 v52, v2
	v_mov_b32_e32 v53, v2
	v_mov_b32_e32 v54, v2
	v_mov_b32_e32 v55, v2
	v_mov_b32_e32 v56, v2
	v_mov_b32_e32 v57, v2
	v_mov_b32_e32 v58, v2
	v_mov_b32_e32 v59, v2
	v_mov_b32_e32 v60, v2
	v_mov_b32_e32 v61, v2
	v_mov_b32_e32 v62, v2
	v_mov_b32_e32 v63, v2
	v_mov_b32_e32 v64, v2
	v_mov_b32_e32 v65, v2
	v_mov_b32_e32 v98, v2
	v_mov_b32_e32 v99, v2
	v_mov_b32_e32 v100, v2
	v_mov_b32_e32 v101, v2
	v_mov_b32_e32 v102, v2
	v_mov_b32_e32 v103, v2
	v_mov_b32_e32 v104, v2
	v_mov_b32_e32 v105, v2
	v_mov_b32_e32 v106, v2
	v_mov_b32_e32 v107, v2
	v_mov_b32_e32 v108, v2
	v_mov_b32_e32 v109, v2
	v_mov_b32_e32 v110, v2
	v_mov_b32_e32 v111, v2
	v_mov_b32_e32 v112, v2
	v_mov_b32_e32 v113, v2
	v_mov_b32_e32 v114, v2
	v_mov_b32_e32 v115, v2
	v_mov_b32_e32 v116, v2
	v_mov_b32_e32 v117, v2
	v_mov_b32_e32 v118, v2
	v_mov_b32_e32 v119, v2
	v_mov_b32_e32 v120, v2
	v_mov_b32_e32 v121, v2
	v_mov_b32_e32 v122, v2
	v_mov_b32_e32 v123, v2
	v_mov_b32_e32 v124, v2
	v_mov_b32_e32 v125, v2
	v_mov_b32_e32 v126, v2
	v_mov_b32_e32 v127, v2
	v_mov_b32_e32 v128, v2
	v_mov_b32_e32 v129, v2
	s_branch .LBB0_471

.LBB0_691:
	s_ashr_i32 s15, s14, 31
	s_lshl_b64 s[16:17], s[14:15], 19
	s_add_u32 s16, s82, s16
	s_addc_u32 s17, s83, s17
	s_and_b64 s[18:19], s[6:7], exec
	s_cselect_b32 s15, s17, s5
	s_cselect_b32 s46, s16, s4
	s_ashr_i32 s11, s10, 31
	s_lshl_b64 s[18:19], s[10:11], 19
	s_add_u32 s18, s34, s18
	s_addc_u32 s19, s35, s19
	s_and_b64 s[28:29], s[6:7], exec
	s_cselect_b32 s11, s19, s21
	s_cselect_b32 s47, s18, s20
	s_add_u32 s4, s4, 0x40080
	s_addc_u32 s5, s5, 0
	s_add_u32 s48, s20, 0x100
	s_addc_u32 s49, s21, 0
	s_mov_b32 s50, -2
	s_add_u32 s20, s4, 0xfffc0080
	s_addc_u32 s21, s5, -1
	s_add_i32 s51, 0, 0x10000
	s_cmp_eq_u32 s50, 12
	s_cselect_b32 s29, s15, s21
	s_cselect_b32 s28, s46, s20
	v_add_u32_e32 v140, s51, v143
	s_cselect_b32 s21, s11, s49
	s_cselect_b32 s20, s47, s48
	s_add_i32 s54, 0, 0x14000
	ds_read_b128 v[146:149], v140
	ds_read_b128 v[150:153], v140 offset:1024
	ds_read_b128 v[154:157], v140 offset:2048
	ds_read_b128 v[158:161], v140 offset:3072
	v_add_u32_e32 v140, s54, v143
	ds_read_b128 v[162:165], v140
	ds_read_b128 v[166:169], v140 offset:1024
	ds_read_b128 v[170:173], v140 offset:2048
	ds_read_b128 v[174:177], v140 offset:3072
	v_lshl_add_u64 v[140:141], s[4:5], 0, v[136:137]
	s_add_i32 m0, s38, 0xc000
	ds_read_b128 v[178:181], v145
	ds_read_b128 v[182:185], v145 offset:1024
	ds_read_b128 v[186:189], v145 offset:2048
	ds_read_b128 v[190:193], v145 offset:3072
	ds_read_b128 v[202:205], v145 offset:4096
	ds_read_b128 v[206:209], v145 offset:5120
	ds_read_b128 v[220:223], v145 offset:6144
	ds_read_b128 v[224:227], v145 offset:7168
	global_load_lds_dwordx4 v[140:141], off
	v_lshl_add_u64 v[140:141], s[4:5], 0, v[138:139]
	s_add_i32 m0, s38, 0xe000
	s_nop 0
	global_load_lds_dwordx4 v[140:141], off
	s_waitcnt vmcnt(8)
	s_waitcnt lgkmcnt(0)
	s_setprio 1
	s_barrier
	v_mfma_f32_16x16x32_bf16 v[126:129], v[146:149], v[178:181], 0
	v_mfma_f32_16x16x32_bf16 v[118:121], v[154:157], v[178:181], 0
	v_mfma_f32_16x16x32_bf16 v[110:113], v[146:149], v[186:189], 0
	v_mfma_f32_16x16x32_bf16 v[102:105], v[154:157], v[186:189], 0
	v_mfma_f32_16x16x32_bf16 v[94:97], v[146:149], v[202:205], 0
	v_mfma_f32_16x16x32_bf16 v[86:89], v[154:157], v[202:205], 0
	v_mfma_f32_16x16x32_bf16 v[78:81], v[146:149], v[220:223], 0
	v_mfma_f32_16x16x32_bf16 v[70:73], v[154:157], v[220:223], 0
	v_mfma_f32_16x16x32_bf16 v[126:129], v[150:153], v[182:185], v[126:129]
	v_mfma_f32_16x16x32_bf16 v[118:121], v[158:161], v[182:185], v[118:121]
	v_mfma_f32_16x16x32_bf16 v[110:113], v[150:153], v[190:193], v[110:113]
	v_mfma_f32_16x16x32_bf16 v[102:105], v[158:161], v[190:193], v[102:105]
	v_mfma_f32_16x16x32_bf16 v[94:97], v[150:153], v[206:209], v[94:97]
	v_mfma_f32_16x16x32_bf16 v[86:89], v[158:161], v[206:209], v[86:89]
	v_mfma_f32_16x16x32_bf16 v[78:81], v[150:153], v[224:227], v[78:81]
	v_mfma_f32_16x16x32_bf16 v[70:73], v[158:161], v[224:227], v[70:73]
	v_mfma_f32_16x16x32_bf16 v[122:125], v[162:165], v[178:181], 0
	v_mfma_f32_16x16x32_bf16 v[114:117], v[170:173], v[178:181], 0
	v_mfma_f32_16x16x32_bf16 v[106:109], v[162:165], v[186:189], 0
	v_mfma_f32_16x16x32_bf16 v[98:101], v[170:173], v[186:189], 0
	v_mfma_f32_16x16x32_bf16 v[90:93], v[162:165], v[202:205], 0
	v_mfma_f32_16x16x32_bf16 v[82:85], v[170:173], v[202:205], 0
	v_mfma_f32_16x16x32_bf16 v[74:77], v[162:165], v[220:223], 0
	v_mfma_f32_16x16x32_bf16 v[66:69], v[170:173], v[220:223], 0
	v_mfma_f32_16x16x32_bf16 v[122:125], v[166:169], v[182:185], v[122:125]
	v_mfma_f32_16x16x32_bf16 v[114:117], v[174:177], v[182:185], v[114:117]
	v_mfma_f32_16x16x32_bf16 v[106:109], v[166:169], v[190:193], v[106:109]
	v_mfma_f32_16x16x32_bf16 v[98:101], v[174:177], v[190:193], v[98:101]
	v_mfma_f32_16x16x32_bf16 v[90:93], v[166:169], v[206:209], v[90:93]
	v_mfma_f32_16x16x32_bf16 v[82:85], v[174:177], v[206:209], v[82:85]
	v_mfma_f32_16x16x32_bf16 v[74:77], v[166:169], v[224:227], v[74:77]
	v_mfma_f32_16x16x32_bf16 v[66:69], v[174:177], v[224:227], v[66:69]
	s_setprio 0
	s_barrier
	s_add_i32 s51, s51, s36
	v_lshl_add_u64 v[140:141], s[20:21], 0, v[0:1]
	s_mov_b32 m0, s51
	ds_read_b128 v[178:181], v145 offset:16384
	ds_read_b128 v[182:185], v145 offset:17408
	ds_read_b128 v[186:189], v145 offset:18432
	ds_read_b128 v[190:193], v145 offset:19456
	ds_read_b128 v[202:205], v145 offset:20480
	ds_read_b128 v[206:209], v145 offset:21504
	ds_read_b128 v[220:223], v145 offset:22528
	ds_read_b128 v[224:227], v145 offset:23552
	global_load_lds_dwordx4 v[140:141], off
	s_add_i32 m0, s51, 0x2000
	s_add_u32 s52, s20, 0x40000
	v_lshl_add_u64 v[194:195], s[20:21], 0, v[130:131]
	s_addc_u32 s53, s21, 0
	s_add_i32 s51, s54, s36
	global_load_lds_dwordx4 v[194:195], off
	v_lshl_add_u64 v[198:199], s[52:53], 0, v[0:1]
	s_mov_b32 m0, s51
	v_lshl_add_u64 v[200:201], s[28:29], 0, v[132:133]
	global_load_lds_dwordx4 v[198:199], off
	v_lshl_add_u64 v[198:199], s[52:53], 0, v[130:131]
	s_add_i32 m0, s51, 0x2000
	s_nop 0
	global_load_lds_dwordx4 v[198:199], off
	v_lshl_add_u64 v[198:199], s[28:29], 0, v[134:135]
	s_mov_b32 m0, s38
	s_nop 0
	global_load_lds_dwordx4 v[198:199], off
	s_mov_b32 m0, s39
	s_nop 0
	global_load_lds_dwordx4 v[200:201], off
	s_waitcnt vmcnt(8)
	s_waitcnt lgkmcnt(0)
	s_setprio 1
	s_barrier
	v_mfma_f32_16x16x32_bf16 v[62:65], v[146:149], v[178:181], 0
	v_mfma_f32_16x16x32_bf16 v[54:57], v[154:157], v[178:181], 0
	v_mfma_f32_16x16x32_bf16 v[46:49], v[146:149], v[186:189], 0
	v_mfma_f32_16x16x32_bf16 v[38:41], v[154:157], v[186:189], 0
	v_mfma_f32_16x16x32_bf16 v[30:33], v[146:149], v[202:205], 0
	v_mfma_f32_16x16x32_bf16 v[22:25], v[154:157], v[202:205], 0
	v_mfma_f32_16x16x32_bf16 v[14:17], v[146:149], v[220:223], 0
	v_mfma_f32_16x16x32_bf16 v[6:9], v[154:157], v[220:223], 0
	v_mfma_f32_16x16x32_bf16 v[62:65], v[150:153], v[182:185], v[62:65]
	v_mfma_f32_16x16x32_bf16 v[54:57], v[158:161], v[182:185], v[54:57]
	v_mfma_f32_16x16x32_bf16 v[46:49], v[150:153], v[190:193], v[46:49]
	v_mfma_f32_16x16x32_bf16 v[38:41], v[158:161], v[190:193], v[38:41]
	v_mfma_f32_16x16x32_bf16 v[30:33], v[150:153], v[206:209], v[30:33]
	v_mfma_f32_16x16x32_bf16 v[22:25], v[158:161], v[206:209], v[22:25]
	v_mfma_f32_16x16x32_bf16 v[14:17], v[150:153], v[224:227], v[14:17]
	v_mfma_f32_16x16x32_bf16 v[6:9], v[158:161], v[224:227], v[6:9]
	v_mfma_f32_16x16x32_bf16 v[58:61], v[162:165], v[178:181], 0
	v_mfma_f32_16x16x32_bf16 v[50:53], v[170:173], v[178:181], 0
	v_mfma_f32_16x16x32_bf16 v[42:45], v[162:165], v[186:189], 0
	v_mfma_f32_16x16x32_bf16 v[34:37], v[170:173], v[186:189], 0
	v_mfma_f32_16x16x32_bf16 v[26:29], v[162:165], v[202:205], 0
	v_mfma_f32_16x16x32_bf16 v[18:21], v[170:173], v[202:205], 0
	v_mfma_f32_16x16x32_bf16 v[10:13], v[162:165], v[220:223], 0
	v_mfma_f32_16x16x32_bf16 v[2:5], v[170:173], v[220:223], 0
	v_mfma_f32_16x16x32_bf16 v[58:61], v[166:169], v[182:185], v[58:61]
	v_mfma_f32_16x16x32_bf16 v[50:53], v[174:177], v[182:185], v[50:53]
	v_mfma_f32_16x16x32_bf16 v[42:45], v[166:169], v[190:193], v[42:45]
	v_mfma_f32_16x16x32_bf16 v[34:37], v[174:177], v[190:193], v[34:37]
	v_mfma_f32_16x16x32_bf16 v[26:29], v[166:169], v[206:209], v[26:29]
	v_mfma_f32_16x16x32_bf16 v[18:21], v[174:177], v[206:209], v[18:21]
	v_mfma_f32_16x16x32_bf16 v[10:13], v[166:169], v[224:227], v[10:13]
	v_mfma_f32_16x16x32_bf16 v[2:5], v[174:177], v[224:227], v[2:5]
	s_setprio 0
	s_barrier
	s_add_i32 s51, 0, 0x18000
	s_add_i32 s52, 0, 0x1c000
	v_add_u32_e32 v158, s51, v143
	v_add_u32_e32 v174, s52, v143
	ds_read_b128 v[146:149], v158
	ds_read_b128 v[150:153], v158 offset:1024
	ds_read_b128 v[154:157], v158 offset:2048
	ds_read_b128 v[158:161], v158 offset:3072
	ds_read_b128 v[162:165], v174
	ds_read_b128 v[166:169], v174 offset:1024
	ds_read_b128 v[170:173], v174 offset:2048
	ds_read_b128 v[174:177], v174 offset:3072
	s_add_u32 s28, s28, 0x40000
	s_addc_u32 s29, s29, 0
	s_mov_b32 m0, s40
	v_lshl_add_u64 v[210:211], s[28:29], 0, v[134:135]
	ds_read_b128 v[178:181], v145 offset:32768
	ds_read_b128 v[182:185], v145 offset:33792
	ds_read_b128 v[186:189], v145 offset:34816
	ds_read_b128 v[190:193], v145 offset:35840
	ds_read_b128 v[202:205], v145 offset:36864
	ds_read_b128 v[206:209], v145 offset:37888
	ds_read_b128 v[220:223], v145 offset:38912
	ds_read_b128 v[224:227], v145 offset:39936
	global_load_lds_dwordx4 v[210:211], off
	v_lshl_add_u64 v[210:211], s[28:29], 0, v[132:133]
	s_mov_b32 m0, s41
	s_nop 0
	global_load_lds_dwordx4 v[210:211], off
	s_waitcnt vmcnt(8)
	s_waitcnt lgkmcnt(0)
	s_setprio 1
	s_barrier
	v_mfma_f32_16x16x32_bf16 v[126:129], v[146:149], v[178:181], v[126:129]
	v_mfma_f32_16x16x32_bf16 v[118:121], v[154:157], v[178:181], v[118:121]
	v_mfma_f32_16x16x32_bf16 v[110:113], v[146:149], v[186:189], v[110:113]
	v_mfma_f32_16x16x32_bf16 v[102:105], v[154:157], v[186:189], v[102:105]
	v_mfma_f32_16x16x32_bf16 v[94:97], v[146:149], v[202:205], v[94:97]
	v_mfma_f32_16x16x32_bf16 v[86:89], v[154:157], v[202:205], v[86:89]
	v_mfma_f32_16x16x32_bf16 v[78:81], v[146:149], v[220:223], v[78:81]
	v_mfma_f32_16x16x32_bf16 v[70:73], v[154:157], v[220:223], v[70:73]
	v_mfma_f32_16x16x32_bf16 v[126:129], v[150:153], v[182:185], v[126:129]
	v_mfma_f32_16x16x32_bf16 v[118:121], v[158:161], v[182:185], v[118:121]
	v_mfma_f32_16x16x32_bf16 v[110:113], v[150:153], v[190:193], v[110:113]
	v_mfma_f32_16x16x32_bf16 v[102:105], v[158:161], v[190:193], v[102:105]
	v_mfma_f32_16x16x32_bf16 v[94:97], v[150:153], v[206:209], v[94:97]
	v_mfma_f32_16x16x32_bf16 v[86:89], v[158:161], v[206:209], v[86:89]
	v_mfma_f32_16x16x32_bf16 v[78:81], v[150:153], v[224:227], v[78:81]
	v_mfma_f32_16x16x32_bf16 v[70:73], v[158:161], v[224:227], v[70:73]
	v_mfma_f32_16x16x32_bf16 v[122:125], v[162:165], v[178:181], v[122:125]
	v_mfma_f32_16x16x32_bf16 v[114:117], v[170:173], v[178:181], v[114:117]
	v_mfma_f32_16x16x32_bf16 v[106:109], v[162:165], v[186:189], v[106:109]
	v_mfma_f32_16x16x32_bf16 v[98:101], v[170:173], v[186:189], v[98:101]
	v_mfma_f32_16x16x32_bf16 v[90:93], v[162:165], v[202:205], v[90:93]
	v_mfma_f32_16x16x32_bf16 v[82:85], v[170:173], v[202:205], v[82:85]
	v_mfma_f32_16x16x32_bf16 v[74:77], v[162:165], v[220:223], v[74:77]
	v_mfma_f32_16x16x32_bf16 v[66:69], v[170:173], v[220:223], v[66:69]
	v_mfma_f32_16x16x32_bf16 v[122:125], v[166:169], v[182:185], v[122:125]
	v_mfma_f32_16x16x32_bf16 v[114:117], v[174:177], v[182:185], v[114:117]
	v_mfma_f32_16x16x32_bf16 v[106:109], v[166:169], v[190:193], v[106:109]
	v_mfma_f32_16x16x32_bf16 v[98:101], v[174:177], v[190:193], v[98:101]
	v_mfma_f32_16x16x32_bf16 v[90:93], v[166:169], v[206:209], v[90:93]
	v_mfma_f32_16x16x32_bf16 v[82:85], v[174:177], v[206:209], v[82:85]
	v_mfma_f32_16x16x32_bf16 v[74:77], v[166:169], v[224:227], v[74:77]
	v_mfma_f32_16x16x32_bf16 v[66:69], v[174:177], v[224:227], v[66:69]
	s_setprio 0
	s_barrier
	s_add_i32 s28, s51, s36
	v_lshl_add_u64 v[140:141], v[140:141], 0, s[84:85]
	s_mov_b32 m0, s28
	ds_read_b128 v[178:181], v145 offset:49152
	ds_read_b128 v[182:185], v145 offset:50176
	ds_read_b128 v[186:189], v145 offset:51200
	ds_read_b128 v[190:193], v145 offset:52224
	ds_read_b128 v[202:205], v145 offset:53248
	ds_read_b128 v[206:209], v145 offset:54272
	ds_read_b128 v[220:223], v145 offset:55296
	ds_read_b128 v[224:227], v145 offset:56320
	global_load_lds_dwordx4 v[140:141], off
	s_add_i32 m0, s28, 0x2000
	s_add_u32 s20, s20, 0x40080
	v_lshl_add_u64 v[140:141], v[194:195], 0, s[84:85]
	s_addc_u32 s21, s21, 0
	s_add_i32 s28, s52, s36
	global_load_lds_dwordx4 v[140:141], off
	v_lshl_add_u64 v[140:141], s[20:21], 0, v[0:1]
	s_mov_b32 m0, s28
	s_nop 0
	global_load_lds_dwordx4 v[140:141], off
	v_lshl_add_u64 v[140:141], s[20:21], 0, v[130:131]
	s_add_i32 m0, s28, 0x2000
	s_nop 0
	global_load_lds_dwordx4 v[140:141], off
	v_lshl_add_u64 v[140:141], v[198:199], 0, s[84:85]
	s_mov_b32 m0, s76
	s_nop 0
	global_load_lds_dwordx4 v[140:141], off
	v_lshl_add_u64 v[140:141], v[200:201], 0, s[84:85]
	s_mov_b32 m0, s77
	s_nop 0
	global_load_lds_dwordx4 v[140:141], off
	s_waitcnt vmcnt(8)
	s_waitcnt lgkmcnt(0)
	s_setprio 1
	s_barrier
	v_mfma_f32_16x16x32_bf16 v[62:65], v[146:149], v[178:181], v[62:65]
	v_mfma_f32_16x16x32_bf16 v[54:57], v[154:157], v[178:181], v[54:57]
	v_mfma_f32_16x16x32_bf16 v[46:49], v[146:149], v[186:189], v[46:49]
	v_mfma_f32_16x16x32_bf16 v[38:41], v[154:157], v[186:189], v[38:41]
	v_mfma_f32_16x16x32_bf16 v[30:33], v[146:149], v[202:205], v[30:33]
	v_mfma_f32_16x16x32_bf16 v[22:25], v[154:157], v[202:205], v[22:25]
	v_mfma_f32_16x16x32_bf16 v[14:17], v[146:149], v[220:223], v[14:17]
	v_mfma_f32_16x16x32_bf16 v[6:9], v[154:157], v[220:223], v[6:9]
	v_mfma_f32_16x16x32_bf16 v[62:65], v[150:153], v[182:185], v[62:65]
	v_mfma_f32_16x16x32_bf16 v[54:57], v[158:161], v[182:185], v[54:57]
	v_mfma_f32_16x16x32_bf16 v[46:49], v[150:153], v[190:193], v[46:49]
	v_mfma_f32_16x16x32_bf16 v[38:41], v[158:161], v[190:193], v[38:41]
	v_mfma_f32_16x16x32_bf16 v[30:33], v[150:153], v[206:209], v[30:33]
	v_mfma_f32_16x16x32_bf16 v[22:25], v[158:161], v[206:209], v[22:25]
	v_mfma_f32_16x16x32_bf16 v[14:17], v[150:153], v[224:227], v[14:17]
	v_mfma_f32_16x16x32_bf16 v[6:9], v[158:161], v[224:227], v[6:9]
	v_mfma_f32_16x16x32_bf16 v[58:61], v[162:165], v[178:181], v[58:61]
	v_mfma_f32_16x16x32_bf16 v[50:53], v[170:173], v[178:181], v[50:53]
	v_mfma_f32_16x16x32_bf16 v[42:45], v[162:165], v[186:189], v[42:45]
	v_mfma_f32_16x16x32_bf16 v[34:37], v[170:173], v[186:189], v[34:37]
	v_mfma_f32_16x16x32_bf16 v[26:29], v[162:165], v[202:205], v[26:29]
	v_mfma_f32_16x16x32_bf16 v[18:21], v[170:173], v[202:205], v[18:21]
	v_mfma_f32_16x16x32_bf16 v[10:13], v[162:165], v[220:223], v[10:13]
	v_mfma_f32_16x16x32_bf16 v[2:5], v[170:173], v[220:223], v[2:5]
	v_mfma_f32_16x16x32_bf16 v[58:61], v[166:169], v[182:185], v[58:61]
	v_mfma_f32_16x16x32_bf16 v[50:53], v[174:177], v[182:185], v[50:53]
	v_mfma_f32_16x16x32_bf16 v[42:45], v[166:169], v[190:193], v[42:45]
	v_mfma_f32_16x16x32_bf16 v[34:37], v[174:177], v[190:193], v[34:37]
	v_mfma_f32_16x16x32_bf16 v[26:29], v[166:169], v[206:209], v[26:29]
	v_mfma_f32_16x16x32_bf16 v[18:21], v[174:177], v[206:209], v[18:21]
	v_mfma_f32_16x16x32_bf16 v[10:13], v[166:169], v[224:227], v[10:13]
	v_mfma_f32_16x16x32_bf16 v[2:5], v[174:177], v[224:227], v[2:5]
	s_setprio 0
	s_barrier
	s_add_i32 s50, s50, 2
	s_add_u32 s4, s4, 0x100
	s_addc_u32 s5, s5, 0
	s_add_u32 s48, s48, 0x100
	s_addc_u32 s49, s49, 0
	s_cmp_gt_u32 s50, 13
	s_cbranch_scc1 .Lpeel_exit_swi
.LBB0_692:
	s_add_u32 s20, s4, 0xfffc0080
	s_addc_u32 s21, s5, -1
	s_add_i32 s51, 0, 0x10000
	s_cmp_eq_u32 s50, 12
	s_cselect_b32 s29, s15, s21
	s_cselect_b32 s28, s46, s20
	v_add_u32_e32 v140, s51, v143
	s_cselect_b32 s21, s11, s49
	s_cselect_b32 s20, s47, s48
	s_add_i32 s54, 0, 0x14000
	ds_read_b128 v[146:149], v140
	ds_read_b128 v[150:153], v140 offset:1024
	ds_read_b128 v[154:157], v140 offset:2048
	ds_read_b128 v[158:161], v140 offset:3072
	v_add_u32_e32 v140, s54, v143
	ds_read_b128 v[162:165], v140
	ds_read_b128 v[166:169], v140 offset:1024
	ds_read_b128 v[170:173], v140 offset:2048
	ds_read_b128 v[174:177], v140 offset:3072
	v_lshl_add_u64 v[140:141], s[4:5], 0, v[136:137]
	s_add_i32 m0, s38, 0xc000
	ds_read_b128 v[178:181], v145
	ds_read_b128 v[182:185], v145 offset:1024
	ds_read_b128 v[186:189], v145 offset:2048
	ds_read_b128 v[190:193], v145 offset:3072
	ds_read_b128 v[202:205], v145 offset:4096
	ds_read_b128 v[206:209], v145 offset:5120
	ds_read_b128 v[220:223], v145 offset:6144
	ds_read_b128 v[224:227], v145 offset:7168
	global_load_lds_dwordx4 v[140:141], off
	v_lshl_add_u64 v[140:141], s[4:5], 0, v[138:139]
	s_add_i32 m0, s38, 0xe000
	s_nop 0
	global_load_lds_dwordx4 v[140:141], off
	s_waitcnt vmcnt(8)
	s_waitcnt lgkmcnt(0)
	s_setprio 1
	s_barrier
	v_mfma_f32_16x16x32_bf16 v[126:129], v[146:149], v[178:181], v[126:129]
	v_mfma_f32_16x16x32_bf16 v[118:121], v[154:157], v[178:181], v[118:121]
	v_mfma_f32_16x16x32_bf16 v[110:113], v[146:149], v[186:189], v[110:113]
	v_mfma_f32_16x16x32_bf16 v[102:105], v[154:157], v[186:189], v[102:105]
	v_mfma_f32_16x16x32_bf16 v[94:97], v[146:149], v[202:205], v[94:97]
	v_mfma_f32_16x16x32_bf16 v[86:89], v[154:157], v[202:205], v[86:89]
	v_mfma_f32_16x16x32_bf16 v[78:81], v[146:149], v[220:223], v[78:81]
	v_mfma_f32_16x16x32_bf16 v[70:73], v[154:157], v[220:223], v[70:73]
	v_mfma_f32_16x16x32_bf16 v[126:129], v[150:153], v[182:185], v[126:129]
	v_mfma_f32_16x16x32_bf16 v[118:121], v[158:161], v[182:185], v[118:121]
	v_mfma_f32_16x16x32_bf16 v[110:113], v[150:153], v[190:193], v[110:113]
	v_mfma_f32_16x16x32_bf16 v[102:105], v[158:161], v[190:193], v[102:105]
	v_mfma_f32_16x16x32_bf16 v[94:97], v[150:153], v[206:209], v[94:97]
	v_mfma_f32_16x16x32_bf16 v[86:89], v[158:161], v[206:209], v[86:89]
	v_mfma_f32_16x16x32_bf16 v[78:81], v[150:153], v[224:227], v[78:81]
	v_mfma_f32_16x16x32_bf16 v[70:73], v[158:161], v[224:227], v[70:73]
	v_mfma_f32_16x16x32_bf16 v[122:125], v[162:165], v[178:181], v[122:125]
	v_mfma_f32_16x16x32_bf16 v[114:117], v[170:173], v[178:181], v[114:117]
	v_mfma_f32_16x16x32_bf16 v[106:109], v[162:165], v[186:189], v[106:109]
	v_mfma_f32_16x16x32_bf16 v[98:101], v[170:173], v[186:189], v[98:101]
	v_mfma_f32_16x16x32_bf16 v[90:93], v[162:165], v[202:205], v[90:93]
	v_mfma_f32_16x16x32_bf16 v[82:85], v[170:173], v[202:205], v[82:85]
	v_mfma_f32_16x16x32_bf16 v[74:77], v[162:165], v[220:223], v[74:77]
	v_mfma_f32_16x16x32_bf16 v[66:69], v[170:173], v[220:223], v[66:69]
	v_mfma_f32_16x16x32_bf16 v[122:125], v[166:169], v[182:185], v[122:125]
	v_mfma_f32_16x16x32_bf16 v[114:117], v[174:177], v[182:185], v[114:117]
	v_mfma_f32_16x16x32_bf16 v[106:109], v[166:169], v[190:193], v[106:109]
	v_mfma_f32_16x16x32_bf16 v[98:101], v[174:177], v[190:193], v[98:101]
	v_mfma_f32_16x16x32_bf16 v[90:93], v[166:169], v[206:209], v[90:93]
	v_mfma_f32_16x16x32_bf16 v[82:85], v[174:177], v[206:209], v[82:85]
	v_mfma_f32_16x16x32_bf16 v[74:77], v[166:169], v[224:227], v[74:77]
	v_mfma_f32_16x16x32_bf16 v[66:69], v[174:177], v[224:227], v[66:69]
	s_setprio 0
	s_barrier
	s_add_i32 s51, s51, s36
	v_lshl_add_u64 v[140:141], s[20:21], 0, v[0:1]
	s_mov_b32 m0, s51
	ds_read_b128 v[178:181], v145 offset:16384
	ds_read_b128 v[182:185], v145 offset:17408
	ds_read_b128 v[186:189], v145 offset:18432
	ds_read_b128 v[190:193], v145 offset:19456
	ds_read_b128 v[202:205], v145 offset:20480
	ds_read_b128 v[206:209], v145 offset:21504
	ds_read_b128 v[220:223], v145 offset:22528
	ds_read_b128 v[224:227], v145 offset:23552
	global_load_lds_dwordx4 v[140:141], off
	s_add_i32 m0, s51, 0x2000
	s_add_u32 s52, s20, 0x40000
	v_lshl_add_u64 v[194:195], s[20:21], 0, v[130:131]
	s_addc_u32 s53, s21, 0
	s_add_i32 s51, s54, s36
	global_load_lds_dwordx4 v[194:195], off
	v_lshl_add_u64 v[198:199], s[52:53], 0, v[0:1]
	s_mov_b32 m0, s51
	v_lshl_add_u64 v[200:201], s[28:29], 0, v[132:133]
	global_load_lds_dwordx4 v[198:199], off
	v_lshl_add_u64 v[198:199], s[52:53], 0, v[130:131]
	s_add_i32 m0, s51, 0x2000
	s_nop 0
	global_load_lds_dwordx4 v[198:199], off
	v_lshl_add_u64 v[198:199], s[28:29], 0, v[134:135]
	s_mov_b32 m0, s38
	s_nop 0
	global_load_lds_dwordx4 v[198:199], off
	s_mov_b32 m0, s39
	s_nop 0
	global_load_lds_dwordx4 v[200:201], off
	s_waitcnt vmcnt(8)
	s_waitcnt lgkmcnt(0)
	s_setprio 1
	s_barrier
	v_mfma_f32_16x16x32_bf16 v[62:65], v[146:149], v[178:181], v[62:65]
	v_mfma_f32_16x16x32_bf16 v[54:57], v[154:157], v[178:181], v[54:57]
	v_mfma_f32_16x16x32_bf16 v[46:49], v[146:149], v[186:189], v[46:49]
	v_mfma_f32_16x16x32_bf16 v[38:41], v[154:157], v[186:189], v[38:41]
	v_mfma_f32_16x16x32_bf16 v[30:33], v[146:149], v[202:205], v[30:33]
	v_mfma_f32_16x16x32_bf16 v[22:25], v[154:157], v[202:205], v[22:25]
	v_mfma_f32_16x16x32_bf16 v[14:17], v[146:149], v[220:223], v[14:17]
	v_mfma_f32_16x16x32_bf16 v[6:9], v[154:157], v[220:223], v[6:9]
	v_mfma_f32_16x16x32_bf16 v[62:65], v[150:153], v[182:185], v[62:65]
	v_mfma_f32_16x16x32_bf16 v[54:57], v[158:161], v[182:185], v[54:57]
	v_mfma_f32_16x16x32_bf16 v[46:49], v[150:153], v[190:193], v[46:49]
	v_mfma_f32_16x16x32_bf16 v[38:41], v[158:161], v[190:193], v[38:41]
	v_mfma_f32_16x16x32_bf16 v[30:33], v[150:153], v[206:209], v[30:33]
	v_mfma_f32_16x16x32_bf16 v[22:25], v[158:161], v[206:209], v[22:25]
	v_mfma_f32_16x16x32_bf16 v[14:17], v[150:153], v[224:227], v[14:17]
	v_mfma_f32_16x16x32_bf16 v[6:9], v[158:161], v[224:227], v[6:9]
	v_mfma_f32_16x16x32_bf16 v[58:61], v[162:165], v[178:181], v[58:61]
	v_mfma_f32_16x16x32_bf16 v[50:53], v[170:173], v[178:181], v[50:53]
	v_mfma_f32_16x16x32_bf16 v[42:45], v[162:165], v[186:189], v[42:45]
	v_mfma_f32_16x16x32_bf16 v[34:37], v[170:173], v[186:189], v[34:37]
	v_mfma_f32_16x16x32_bf16 v[26:29], v[162:165], v[202:205], v[26:29]
	v_mfma_f32_16x16x32_bf16 v[18:21], v[170:173], v[202:205], v[18:21]
	v_mfma_f32_16x16x32_bf16 v[10:13], v[162:165], v[220:223], v[10:13]
	v_mfma_f32_16x16x32_bf16 v[2:5], v[170:173], v[220:223], v[2:5]
	v_mfma_f32_16x16x32_bf16 v[58:61], v[166:169], v[182:185], v[58:61]
	v_mfma_f32_16x16x32_bf16 v[50:53], v[174:177], v[182:185], v[50:53]
	v_mfma_f32_16x16x32_bf16 v[42:45], v[166:169], v[190:193], v[42:45]
	v_mfma_f32_16x16x32_bf16 v[34:37], v[174:177], v[190:193], v[34:37]
	v_mfma_f32_16x16x32_bf16 v[26:29], v[166:169], v[206:209], v[26:29]
	v_mfma_f32_16x16x32_bf16 v[18:21], v[174:177], v[206:209], v[18:21]
	v_mfma_f32_16x16x32_bf16 v[10:13], v[166:169], v[224:227], v[10:13]
	v_mfma_f32_16x16x32_bf16 v[2:5], v[174:177], v[224:227], v[2:5]
	s_setprio 0
	s_barrier
	s_add_i32 s51, 0, 0x18000
	s_add_i32 s52, 0, 0x1c000
	v_add_u32_e32 v158, s51, v143
	v_add_u32_e32 v174, s52, v143
	ds_read_b128 v[146:149], v158
	ds_read_b128 v[150:153], v158 offset:1024
	ds_read_b128 v[154:157], v158 offset:2048
	ds_read_b128 v[158:161], v158 offset:3072
	ds_read_b128 v[162:165], v174
	ds_read_b128 v[166:169], v174 offset:1024
	ds_read_b128 v[170:173], v174 offset:2048
	ds_read_b128 v[174:177], v174 offset:3072
	s_add_u32 s28, s28, 0x40000
	s_addc_u32 s29, s29, 0
	s_mov_b32 m0, s40
	v_lshl_add_u64 v[210:211], s[28:29], 0, v[134:135]
	ds_read_b128 v[178:181], v145 offset:32768
	ds_read_b128 v[182:185], v145 offset:33792
	ds_read_b128 v[186:189], v145 offset:34816
	ds_read_b128 v[190:193], v145 offset:35840
	ds_read_b128 v[202:205], v145 offset:36864
	ds_read_b128 v[206:209], v145 offset:37888
	ds_read_b128 v[220:223], v145 offset:38912
	ds_read_b128 v[224:227], v145 offset:39936
	global_load_lds_dwordx4 v[210:211], off
	v_lshl_add_u64 v[210:211], s[28:29], 0, v[132:133]
	s_mov_b32 m0, s41
	s_nop 0
	global_load_lds_dwordx4 v[210:211], off
	s_waitcnt vmcnt(8)
	s_waitcnt lgkmcnt(0)
	s_setprio 1
	s_barrier
	v_mfma_f32_16x16x32_bf16 v[126:129], v[146:149], v[178:181], v[126:129]
	v_mfma_f32_16x16x32_bf16 v[118:121], v[154:157], v[178:181], v[118:121]
	v_mfma_f32_16x16x32_bf16 v[110:113], v[146:149], v[186:189], v[110:113]
	v_mfma_f32_16x16x32_bf16 v[102:105], v[154:157], v[186:189], v[102:105]
	v_mfma_f32_16x16x32_bf16 v[94:97], v[146:149], v[202:205], v[94:97]
	v_mfma_f32_16x16x32_bf16 v[86:89], v[154:157], v[202:205], v[86:89]
	v_mfma_f32_16x16x32_bf16 v[78:81], v[146:149], v[220:223], v[78:81]
	v_mfma_f32_16x16x32_bf16 v[70:73], v[154:157], v[220:223], v[70:73]
	v_mfma_f32_16x16x32_bf16 v[126:129], v[150:153], v[182:185], v[126:129]
	v_mfma_f32_16x16x32_bf16 v[118:121], v[158:161], v[182:185], v[118:121]
	v_mfma_f32_16x16x32_bf16 v[110:113], v[150:153], v[190:193], v[110:113]
	v_mfma_f32_16x16x32_bf16 v[102:105], v[158:161], v[190:193], v[102:105]
	v_mfma_f32_16x16x32_bf16 v[94:97], v[150:153], v[206:209], v[94:97]
	v_mfma_f32_16x16x32_bf16 v[86:89], v[158:161], v[206:209], v[86:89]
	v_mfma_f32_16x16x32_bf16 v[78:81], v[150:153], v[224:227], v[78:81]
	v_mfma_f32_16x16x32_bf16 v[70:73], v[158:161], v[224:227], v[70:73]
	v_mfma_f32_16x16x32_bf16 v[122:125], v[162:165], v[178:181], v[122:125]
	v_mfma_f32_16x16x32_bf16 v[114:117], v[170:173], v[178:181], v[114:117]
	v_mfma_f32_16x16x32_bf16 v[106:109], v[162:165], v[186:189], v[106:109]
	v_mfma_f32_16x16x32_bf16 v[98:101], v[170:173], v[186:189], v[98:101]
	v_mfma_f32_16x16x32_bf16 v[90:93], v[162:165], v[202:205], v[90:93]
	v_mfma_f32_16x16x32_bf16 v[82:85], v[170:173], v[202:205], v[82:85]
	v_mfma_f32_16x16x32_bf16 v[74:77], v[162:165], v[220:223], v[74:77]
	v_mfma_f32_16x16x32_bf16 v[66:69], v[170:173], v[220:223], v[66:69]
	v_mfma_f32_16x16x32_bf16 v[122:125], v[166:169], v[182:185], v[122:125]
	v_mfma_f32_16x16x32_bf16 v[114:117], v[174:177], v[182:185], v[114:117]
	v_mfma_f32_16x16x32_bf16 v[106:109], v[166:169], v[190:193], v[106:109]
	v_mfma_f32_16x16x32_bf16 v[98:101], v[174:177], v[190:193], v[98:101]
	v_mfma_f32_16x16x32_bf16 v[90:93], v[166:169], v[206:209], v[90:93]
	v_mfma_f32_16x16x32_bf16 v[82:85], v[174:177], v[206:209], v[82:85]
	v_mfma_f32_16x16x32_bf16 v[74:77], v[166:169], v[224:227], v[74:77]
	v_mfma_f32_16x16x32_bf16 v[66:69], v[174:177], v[224:227], v[66:69]
	s_setprio 0
	s_barrier
	s_add_i32 s28, s51, s36
	v_lshl_add_u64 v[140:141], v[140:141], 0, s[84:85]
	s_mov_b32 m0, s28
	ds_read_b128 v[178:181], v145 offset:49152
	ds_read_b128 v[182:185], v145 offset:50176
	ds_read_b128 v[186:189], v145 offset:51200
	ds_read_b128 v[190:193], v145 offset:52224
	ds_read_b128 v[202:205], v145 offset:53248
	ds_read_b128 v[206:209], v145 offset:54272
	ds_read_b128 v[220:223], v145 offset:55296
	ds_read_b128 v[224:227], v145 offset:56320
	global_load_lds_dwordx4 v[140:141], off
	s_add_i32 m0, s28, 0x2000
	s_add_u32 s20, s20, 0x40080
	v_lshl_add_u64 v[140:141], v[194:195], 0, s[84:85]
	s_addc_u32 s21, s21, 0
	s_add_i32 s28, s52, s36
	global_load_lds_dwordx4 v[140:141], off
	v_lshl_add_u64 v[140:141], s[20:21], 0, v[0:1]
	s_mov_b32 m0, s28
	s_nop 0
	global_load_lds_dwordx4 v[140:141], off
	v_lshl_add_u64 v[140:141], s[20:21], 0, v[130:131]
	s_add_i32 m0, s28, 0x2000
	s_nop 0
	global_load_lds_dwordx4 v[140:141], off
	v_lshl_add_u64 v[140:141], v[198:199], 0, s[84:85]
	s_mov_b32 m0, s76
	s_nop 0
	global_load_lds_dwordx4 v[140:141], off
	v_lshl_add_u64 v[140:141], v[200:201], 0, s[84:85]
	s_mov_b32 m0, s77
	s_nop 0
	global_load_lds_dwordx4 v[140:141], off
	s_waitcnt vmcnt(8)
	s_waitcnt lgkmcnt(0)
	s_setprio 1
	s_barrier
	v_mfma_f32_16x16x32_bf16 v[62:65], v[146:149], v[178:181], v[62:65]
	v_mfma_f32_16x16x32_bf16 v[54:57], v[154:157], v[178:181], v[54:57]
	v_mfma_f32_16x16x32_bf16 v[46:49], v[146:149], v[186:189], v[46:49]
	v_mfma_f32_16x16x32_bf16 v[38:41], v[154:157], v[186:189], v[38:41]
	v_mfma_f32_16x16x32_bf16 v[30:33], v[146:149], v[202:205], v[30:33]
	v_mfma_f32_16x16x32_bf16 v[22:25], v[154:157], v[202:205], v[22:25]
	v_mfma_f32_16x16x32_bf16 v[14:17], v[146:149], v[220:223], v[14:17]
	v_mfma_f32_16x16x32_bf16 v[6:9], v[154:157], v[220:223], v[6:9]
	v_mfma_f32_16x16x32_bf16 v[62:65], v[150:153], v[182:185], v[62:65]
	v_mfma_f32_16x16x32_bf16 v[54:57], v[158:161], v[182:185], v[54:57]
	v_mfma_f32_16x16x32_bf16 v[46:49], v[150:153], v[190:193], v[46:49]
	v_mfma_f32_16x16x32_bf16 v[38:41], v[158:161], v[190:193], v[38:41]
	v_mfma_f32_16x16x32_bf16 v[30:33], v[150:153], v[206:209], v[30:33]
	v_mfma_f32_16x16x32_bf16 v[22:25], v[158:161], v[206:209], v[22:25]
	v_mfma_f32_16x16x32_bf16 v[14:17], v[150:153], v[224:227], v[14:17]
	v_mfma_f32_16x16x32_bf16 v[6:9], v[158:161], v[224:227], v[6:9]
	v_mfma_f32_16x16x32_bf16 v[58:61], v[162:165], v[178:181], v[58:61]
	v_mfma_f32_16x16x32_bf16 v[50:53], v[170:173], v[178:181], v[50:53]
	v_mfma_f32_16x16x32_bf16 v[42:45], v[162:165], v[186:189], v[42:45]
	v_mfma_f32_16x16x32_bf16 v[34:37], v[170:173], v[186:189], v[34:37]
	v_mfma_f32_16x16x32_bf16 v[26:29], v[162:165], v[202:205], v[26:29]
	v_mfma_f32_16x16x32_bf16 v[18:21], v[170:173], v[202:205], v[18:21]
	v_mfma_f32_16x16x32_bf16 v[10:13], v[162:165], v[220:223], v[10:13]
	v_mfma_f32_16x16x32_bf16 v[2:5], v[170:173], v[220:223], v[2:5]
	v_mfma_f32_16x16x32_bf16 v[58:61], v[166:169], v[182:185], v[58:61]
	v_mfma_f32_16x16x32_bf16 v[50:53], v[174:177], v[182:185], v[50:53]
	v_mfma_f32_16x16x32_bf16 v[42:45], v[166:169], v[190:193], v[42:45]
	v_mfma_f32_16x16x32_bf16 v[34:37], v[174:177], v[190:193], v[34:37]
	v_mfma_f32_16x16x32_bf16 v[26:29], v[166:169], v[206:209], v[26:29]
	v_mfma_f32_16x16x32_bf16 v[18:21], v[174:177], v[206:209], v[18:21]
	v_mfma_f32_16x16x32_bf16 v[10:13], v[166:169], v[224:227], v[10:13]
	v_mfma_f32_16x16x32_bf16 v[2:5], v[174:177], v[224:227], v[2:5]
	s_setprio 0
	s_barrier
	s_add_i32 s50, s50, 2
	s_add_u32 s4, s4, 0x100
	s_addc_u32 s5, s5, 0
	s_add_u32 s48, s48, 0x100
	s_addc_u32 s49, s49, 0
	s_cmp_gt_u32 s50, 13
	s_cbranch_scc0 .LBB0_692
